# norm loops fix with next-rows touch skipped in the last iteration
# speedup vs baseline: 1.1002x; 1.0089x over previous
; __device__ __forceinline__ void unpack8(const v4u& w, float (&f)[8]) { f[0] = bflo(w.x); f[1] = bfhi(w.x); f[2] = bflo(w.y); f[3] = bfhi(w.y); f[4] = bflo(w.z); f[5] = bfhi(w.z); f[6] = bflo(w.w); f[7] = bfhi(w.w); }
; template <bool ZP, bool XF32, bool OUT8 = false>
; __device__ __forceinline__ void norm_phase(LAS unsigned char* lds, const void* xin, const float* gain, const float* sh, const float* sc, bf16* hout, const float* wzt, float* zout, int lane, int wave, int vcu, int G) {
;     ...
;     for (int it_ = 0; it_ < nit; ++it_) {
;         const int m0 = xdeal ? 2048 * (gw >> 8) + 2 * (gw & 255) + 512 * it_ : 2 * gw + it_ * 2 * NGW;
;         if (m0 >= M) break;
;         f32x4 v[2][4][2]; float ss[2] = {0.f, 0.f};
; #pragma unroll
;         for (int r = 0; r < 2; ++r)
; #pragma unroll
;             for (int j = 0; j < 4; ++j) {
;                 if constexpr (XF32) { const float* xr = (const float*)xin + (size_t)(m0 + r) * D + 8 * lane; v[r][j][0] = *(const f32x4*)(xr + 512 * j); v[r][j][1] = *(const f32x4*)(xr + 512 * j + 4); }
;                 else { float f[8]; unpack8(*(const v4u*)((const bf16*)xin + (size_t)(m0 + r) * D + 8 * lane + 512 * j), f); v[r][j][0] = (f32x4){f[0], f[1], f[2], f[3]}; v[r][j][1] = (f32x4){f[4], f[5], f[6], f[7]}; } }
; #pragma unroll
;         for (int r = 0; r < 2; ++r)
; #pragma unroll
;             for (int j = 0; j < 4; ++j)
; #pragma unroll
;                 for (int e = 0; e < 4; ++e) ss[r] += v[r][j][0][e] * v[r][j][0][e] + v[r][j][1][e] * v[r][j][1][e];
; #pragma unroll
;         for (int r = 0; r < 2; ++r) { const int m = m0 + r, b = m >> 11;
;             const float rstd = rsqrtf(wave_sum(ss[r]) * (1.0f / D) + EPS);
; #pragma unroll
;             for (int j = 0; j < 4; ++j) { const int col = 512 * j + 8 * lane;
; #pragma unroll
;                 for (int q = 0; q < 2; ++q) { const f32x4 gg = *(const f32x4*)(gain + col + 4 * q), s1 = *(const f32x4*)(sc + (size_t)b * MODW + col + 4 * q), s0 = *(const f32x4*)(sh + (size_t)b * MODW + col + 4 * q);
;                     v[r][j][q] = (v[r][j][q] * rstd * gg) * (s1 + 1.0f) + s0; }
.LBB0_682:
	s_ashr_i32 s15, s14, 31
	s_add_i32 s10, s14, 1
	s_lshl_b64 s[12:13], s[14:15], 12
	s_ashr_i32 s11, s10, 31
	v_lshl_add_u64 v[2:3], v[6:7], 0, s[12:13]
	v_lshl_add_u64 v[244:245], v[2:3], 0, s[100:101]
	s_lshl_b64 s[8:9], s[10:11], 12
	global_load_dwordx4 v[18:21], v[2:3], off offset:1024
	global_load_dwordx4 v[22:25], v[2:3], off offset:3072
	global_load_dwordx4 v[32:35], v[2:3], off
	global_load_dwordx4 v[38:41], v[2:3], off offset:2048
	v_lshl_add_u64 v[26:27], v[6:7], 0, s[8:9]
	v_lshl_add_u64 v[246:247], v[26:27], 0, s[100:101]
	global_load_dwordx4 v[78:81], v[26:27], off offset:1024
	global_load_dwordx4 v[92:95], v[26:27], off
	global_load_dwordx4 v[2:5], v[26:27], off offset:3072
	global_load_dwordx4 v[96:99], v[26:27], off offset:2048
	s_ashr_i32 s0, s14, 11
	s_mul_hi_i32 s1, s0, 0xc000
	s_mul_i32 s0, s0, 0xc000
	s_add_u32 s14, s19, s0
	s_addc_u32 s15, s20, s1
	s_add_u32 s16, s7, s0
	s_addc_u32 s17, s18, s1
	v_cmp_lt_i32_e32 vcc, v86, v85
	s_ashr_i32 s0, s10, 11
	s_mul_hi_i32 s1, s0, 0xc000
	v_cndmask_b32_e32 v82, v84, v86, vcc
	v_lshlrev_b32_e32 v82, 2, v82
	v_cmp_lt_i32_e32 vcc, v87, v85
	s_mul_i32 s0, s0, 0xc000
	s_add_u32 s10, s19, s0
	s_addc_u32 s11, s20, s1
	s_waitcnt vmcnt(0)
	v_lshlrev_b32_e32 v45, 16, v20
	v_lshlrev_b32_e32 v43, 16, v18
	v_lshlrev_b32_e32 v57, 16, v34
	v_and_b32_e32 v61, 0xffff0000, v34
	v_lshlrev_b32_e32 v56, 16, v94
	v_and_b32_e32 v60, 0xffff0000, v94
	v_lshlrev_b32_e32 v55, 16, v32
	v_and_b32_e32 v59, 0xffff0000, v32
	v_lshlrev_b32_e32 v63, 16, v35
	v_and_b32_e32 v26, 0xffff0000, v78
	v_and_b32_e32 v30, 0xffff0000, v80
	v_lshlrev_b32_e32 v54, 16, v92
	v_and_b32_e32 v58, 0xffff0000, v92
	v_lshlrev_b32_e32 v62, 16, v95
	v_lshlrev_b32_e32 v42, 16, v78
	v_lshlrev_b32_e32 v44, 16, v80
	v_lshlrev_b32_e32 v46, 16, v79
	v_and_b32_e32 v48, 0xffff0000, v79
	v_lshlrev_b32_e32 v50, 16, v81
	v_and_b32_e32 v52, 0xffff0000, v81
	v_pk_mul_f32 v[78:79], v[56:57], v[56:57]
	v_pk_mul_f32 v[80:81], v[60:61], v[60:61]
	v_lshlrev_b32_e32 v65, 16, v33
	v_and_b32_e32 v69, 0xffff0000, v35
	v_lshlrev_b32_e32 v64, 16, v93
	v_and_b32_e32 v66, 0xffff0000, v93
	v_and_b32_e32 v68, 0xffff0000, v95
	v_pk_mul_f32 v[92:93], v[62:63], v[62:63]
	v_pk_fma_f32 v[78:79], v[54:55], v[54:55], v[78:79]
	v_pk_fma_f32 v[80:81], v[58:59], v[58:59], v[80:81]
	v_and_b32_e32 v67, 0xffff0000, v33
	v_pk_mul_f32 v[94:95], v[68:69], v[68:69]
	v_pk_fma_f32 v[92:93], v[64:65], v[64:65], v[92:93]
	v_pk_add_f32 v[78:79], v[78:79], v[80:81]
	v_pk_fma_f32 v[80:81], v[66:67], v[66:67], v[94:95]
	v_pk_add_f32 v[78:79], v[92:93], v[78:79]
	v_and_b32_e32 v31, 0xffff0000, v20
	v_pk_add_f32 v[78:79], v[80:81], v[78:79]
	v_pk_mul_f32 v[80:81], v[44:45], v[44:45]
	v_and_b32_e32 v27, 0xffff0000, v18
	v_pk_fma_f32 v[80:81], v[42:43], v[42:43], v[80:81]
	v_lshlrev_b32_e32 v51, 16, v21
	v_pk_add_f32 v[78:79], v[80:81], v[78:79]
	v_pk_mul_f32 v[80:81], v[30:31], v[30:31]
	v_lshlrev_b32_e32 v47, 16, v19
	v_pk_fma_f32 v[80:81], v[26:27], v[26:27], v[80:81]
	v_and_b32_e32 v49, 0xffff0000, v19
	v_and_b32_e32 v18, 0xffff0000, v4
	v_lshlrev_b32_e32 v19, 16, v4
	v_pk_add_f32 v[78:79], v[80:81], v[78:79]
	v_pk_mul_f32 v[80:81], v[50:51], v[50:51]
	v_and_b32_e32 v70, 0xffff0000, v22
	v_lshlrev_b32_e32 v71, 16, v22
	v_and_b32_e32 v72, 0xffff0000, v24
	v_lshlrev_b32_e32 v73, 16, v24
	v_and_b32_e32 v53, 0xffff0000, v21
	v_and_b32_e32 v20, 0xffff0000, v2
	v_lshlrev_b32_e32 v21, 16, v2
	v_lshlrev_b32_e32 v22, 16, v96
	v_and_b32_e32 v24, 0xffff0000, v96
	v_lshlrev_b32_e32 v28, 16, v97
	v_and_b32_e32 v32, 0xffff0000, v97
	v_pk_mul_f32 v[96:97], v[18:19], v[18:19]
	v_pk_fma_f32 v[80:81], v[46:47], v[46:47], v[80:81]
	v_pk_fma_f32 v[116:117], v[20:21], v[20:21], v[96:97]
	v_pk_add_f32 v[96:97], v[80:81], v[78:79]
	global_load_dwordx4 v[128:131], v1, s[14:15] offset:16
	global_load_dwordx4 v[132:135], v1, s[14:15]
	global_load_dwordx4 v[136:139], v[8:9], off offset:16
	global_load_dwordx4 v[140:143], v[8:9], off
	global_load_dwordx4 v[144:147], v1, s[16:17] offset:16
	global_load_dwordx4 v[148:151], v1, s[16:17]
	global_load_dwordx4 v[152:155], v[8:9], off offset:2048
	global_load_dwordx4 v[156:159], v1, s[14:15] offset:2048
	global_load_dwordx4 v[160:163], v1, s[16:17] offset:2048
	global_load_dwordx4 v[164:167], v[8:9], off offset:2064
	global_load_dwordx4 v[168:171], v1, s[14:15] offset:2064
	global_load_dwordx4 v[172:175], v1, s[16:17] offset:2064
	global_load_dwordx4 v[176:179], v[10:11], off
	global_load_dwordx4 v[180:183], v17, s[14:15]
	global_load_dwordx4 v[184:187], v[10:11], off offset:16
	global_load_dwordx4 v[188:191], v17, s[14:15] offset:16
	global_load_dwordx4 v[192:195], v17, s[16:17]
	global_load_dwordx4 v[196:199], v17, s[16:17] offset:16
	global_load_dwordx4 v[200:203], v[12:13], off
	global_load_dwordx4 v[204:207], v83, s[14:15]
	global_load_dwordx4 v[208:211], v[12:13], off offset:16
	global_load_dwordx4 v[212:215], v83, s[14:15] offset:16
	global_load_dwordx4 v[216:219], v83, s[16:17]
	global_load_dwordx4 v[220:223], v83, s[16:17] offset:16
	v_and_b32_e32 v74, 0xffff0000, v23
	v_lshlrev_b32_e32 v75, 16, v23
	v_and_b32_e32 v76, 0xffff0000, v25
	v_lshlrev_b32_e32 v77, 16, v25
	v_lshlrev_b32_e32 v23, 16, v38
	v_and_b32_e32 v25, 0xffff0000, v38
	v_lshlrev_b32_e32 v35, 16, v40
	v_and_b32_e32 v37, 0xffff0000, v40
	v_lshlrev_b32_e32 v34, 16, v98
	v_and_b32_e32 v36, 0xffff0000, v98
	v_lshlrev_b32_e32 v38, 16, v99
	v_and_b32_e32 v40, 0xffff0000, v99
	v_pk_mul_f32 v[98:99], v[52:53], v[52:53]
	v_lshlrev_b32_e32 v29, 16, v39
	v_pk_fma_f32 v[98:99], v[48:49], v[48:49], v[98:99]
	v_and_b32_e32 v33, 0xffff0000, v39
	v_pk_add_f32 v[96:97], v[98:99], v[96:97]
; template <bool ZP, bool XF32, bool OUT8 = false>
; __device__ __forceinline__ void norm_phase(LAS unsigned char* lds, const void* xin, const float* gain, const float* sh, const float* sc, bf16* hout, const float* wzt, float* zout, int lane, int wave, int vcu, int G) {
;     ...
;         for (int r = 0; r < 2; ++r) { const int m = m0 + r, b = m >> 11;
;             const float rstd = rsqrtf(wave_sum(ss[r]) * (1.0f / D) + EPS);
; #pragma unroll
;             for (int j = 0; j < 4; ++j) { const int col = 512 * j + 8 * lane;
; #pragma unroll
;                 for (int q = 0; q < 2; ++q) { const f32x4 gg = *(const f32x4*)(gain + col + 4 * q), s1 = *(const f32x4*)(sc + (size_t)b * MODW + col + 4 * q), s0 = *(const f32x4*)(sh + (size_t)b * MODW + col + 4 * q);
;                     v[r][j][q] = (v[r][j][q] * rstd * gg) * (s1 + 1.0f) + s0; }
	v_pk_mul_f32 v[98:99], v[34:35], v[34:35]
	v_lshlrev_b32_e32 v39, 16, v41
	v_pk_fma_f32 v[98:99], v[22:23], v[22:23], v[98:99]
	v_and_b32_e32 v41, 0xffff0000, v41
	v_pk_add_f32 v[96:97], v[98:99], v[96:97]
	v_pk_mul_f32 v[98:99], v[36:37], v[36:37]
	v_pk_mul_f32 v[100:101], v[72:73], v[72:73]
	v_pk_fma_f32 v[98:99], v[24:25], v[24:25], v[98:99]
	v_pk_mul_f32 v[102:103], v[76:77], v[76:77]
	v_pk_add_f32 v[96:97], v[98:99], v[96:97]
	v_pk_mul_f32 v[98:99], v[38:39], v[38:39]
	v_pk_fma_f32 v[112:113], v[70:71], v[70:71], v[100:101]
	v_pk_fma_f32 v[98:99], v[28:29], v[28:29], v[98:99]
	v_pk_fma_f32 v[114:115], v[74:75], v[74:75], v[102:103]
	v_pk_add_f32 v[96:97], v[98:99], v[96:97]
	v_pk_mul_f32 v[98:99], v[40:41], v[40:41]
	v_mov_b32_e32 v120, v117
	v_pk_fma_f32 v[98:99], v[32:33], v[32:33], v[98:99]
	v_mov_b32_e32 v121, v113
	v_pk_add_f32 v[118:119], v[98:99], v[96:97]
	v_and_b32_e32 v4, 0xffff0000, v5
	v_lshlrev_b32_e32 v5, 16, v5
	v_pk_add_f32 v[118:119], v[120:121], v[118:119]
	v_and_b32_e32 v2, 0xffff0000, v3
	v_lshlrev_b32_e32 v3, 16, v3
	v_pk_mul_f32 v[120:121], v[4:5], v[4:5]
	v_mov_b32_e32 v117, v112
	v_pk_fma_f32 v[120:121], v[2:3], v[2:3], v[120:121]
	v_pk_add_f32 v[112:113], v[116:117], v[118:119]
	v_mov_b32_e32 v116, v121
	v_mov_b32_e32 v117, v115
	v_pk_add_f32 v[112:113], v[116:117], v[112:113]
	v_mov_b32_e32 v121, v114
	v_pk_add_f32 v[112:113], v[120:121], v[112:113]
	ds_bpermute_b32 v115, v82, v113
	ds_bpermute_b32 v114, v82, v112
	v_cndmask_b32_e32 v82, v84, v87, vcc
	v_lshlrev_b32_e32 v82, 2, v82
	v_cmp_lt_i32_e32 vcc, v88, v85
	v_mov_b32_e32 v122, v35
	s_waitcnt lgkmcnt(0)
	v_pk_add_f32 v[112:113], v[112:113], v[114:115]
	ds_bpermute_b32 v115, v82, v113
	ds_bpermute_b32 v114, v82, v112
	v_cndmask_b32_e32 v82, v84, v88, vcc
	v_lshlrev_b32_e32 v82, 2, v82
	v_cmp_lt_i32_e32 vcc, v89, v85
	v_mov_b32_e32 v123, v37
	s_waitcnt lgkmcnt(0)
	v_pk_add_f32 v[112:113], v[112:113], v[114:115]
	ds_bpermute_b32 v115, v82, v113
	ds_bpermute_b32 v114, v82, v112
	v_cndmask_b32_e32 v82, v84, v89, vcc
	v_lshlrev_b32_e32 v82, 2, v82
	v_cmp_lt_i32_e32 vcc, v90, v85
	v_mov_b32_e32 v120, v39
	s_waitcnt lgkmcnt(0)
	v_pk_add_f32 v[112:113], v[112:113], v[114:115]
	ds_bpermute_b32 v115, v82, v113
	ds_bpermute_b32 v114, v82, v112
	v_cndmask_b32_e32 v82, v84, v90, vcc
	v_lshlrev_b32_e32 v82, 2, v82
	v_cmp_lt_i32_e32 vcc, v91, v85
	s_waitcnt vmcnt(0)
	v_mov_b64_e32 v[92:93], v[128:129]
	v_mov_b64_e32 v[94:95], v[130:131]
	v_mov_b64_e32 v[78:79], v[132:133]
	v_mov_b64_e32 v[80:81], v[134:135]
	v_mov_b64_e32 v[96:97], v[136:137]
	v_mov_b64_e32 v[98:99], v[138:139]
	v_mov_b64_e32 v[100:101], v[140:141]
	v_mov_b64_e32 v[102:103], v[142:143]
	v_mov_b64_e32 v[104:105], v[144:145]
	v_mov_b64_e32 v[106:107], v[146:147]
	v_mov_b64_e32 v[108:109], v[148:149]
	v_mov_b64_e32 v[110:111], v[150:151]
	s_cmp_lg_u32 s3, 1
	s_cbranch_scc0 .Lnorm_nt_LBB0_679
	global_load_dwordx4 v[248:251], v[244:245], off offset:1024
	global_load_dwordx4 v[248:251], v[244:245], off offset:3072
	global_load_dwordx4 v[248:251], v[244:245], off
	global_load_dwordx4 v[248:251], v[244:245], off offset:2048
	global_load_dwordx4 v[248:251], v[246:247], off offset:1024
	global_load_dwordx4 v[248:251], v[246:247], off
	global_load_dwordx4 v[248:251], v[246:247], off offset:3072
	global_load_dwordx4 v[248:251], v[246:247], off offset:2048
.Lnorm_nt_LBB0_679:
	v_pk_add_f32 v[94:95], v[94:95], 1.0 op_sel_hi:[1,0]
	s_waitcnt lgkmcnt(0)
	v_pk_add_f32 v[112:113], v[112:113], v[114:115]
	ds_bpermute_b32 v115, v82, v113
	ds_bpermute_b32 v114, v82, v112
	v_cndmask_b32_e32 v82, v84, v91, vcc
	v_lshlrev_b32_e32 v82, 2, v82
	v_pk_add_f32 v[118:119], v[78:79], 1.0 op_sel_hi:[1,0]
	v_pk_add_f32 v[116:117], v[80:81], 1.0 op_sel_hi:[1,0]
	s_waitcnt lgkmcnt(0)
	v_pk_add_f32 v[112:113], v[112:113], v[114:115]
	ds_bpermute_b32 v115, v82, v113
	ds_bpermute_b32 v114, v82, v112
	v_pk_add_f32 v[92:93], v[92:93], 1.0 op_sel_hi:[1,0]
	v_mov_b32_e32 v121, v41
	v_pk_mov_b32 v[74:75], v[74:75], v[74:75] op_sel:[1,0]
	v_pk_mov_b32 v[76:77], v[76:77], v[76:77] op_sel:[1,0]
	s_waitcnt lgkmcnt(0)
	v_pk_add_f32 v[78:79], v[112:113], v[114:115]
	v_mov_b32_e32 v114, v55
	v_pk_fma_f32 v[78:79], v[78:79], s[6:7], v[16:17] op_sel_hi:[1,0,0]
	v_mov_b32_e32 v115, v59
	v_mul_f32_e32 v80, 0x4b800000, v79
	v_cmp_gt_f32_e32 vcc, s26, v79
	v_mov_b32_e32 v112, v65
	v_mov_b32_e32 v113, v67
	v_cndmask_b32_e32 v79, v79, v80, vcc
	v_rsq_f32_e32 v79, v79
	v_lshl_add_u64 v[80:81], v[14:15], 0, s[12:13]
	s_add_u32 s12, s7, s0
	s_addc_u32 s13, s18, s1
	v_mul_f32_e32 v82, 0x45800000, v79
	v_cndmask_b32_e32 v82, v79, v82, vcc
	v_pk_mul_f32 v[114:115], v[82:83], v[114:115] op_sel_hi:[0,1]
	v_pk_mul_f32 v[112:113], v[82:83], v[112:113] op_sel_hi:[0,1]
	v_pk_mul_f32 v[122:123], v[82:83], v[122:123] op_sel_hi:[0,1]
	v_pk_mul_f32 v[120:121], v[82:83], v[120:121] op_sel_hi:[0,1]
	v_pk_mul_f32 v[76:77], v[82:83], v[76:77] op_sel_hi:[0,1]
	v_cmp_gt_f32_e32 vcc, s26, v78
	v_mov_b32_e32 v65, v66
	v_pk_mul_f32 v[100:101], v[100:101], v[114:115]
	v_pk_mul_f32 v[102:103], v[102:103], v[112:113]
	v_pk_fma_f32 v[100:101], v[118:119], v[100:101], v[108:109]
	v_pk_fma_f32 v[102:103], v[116:117], v[102:103], v[110:111]
	v_mov_b32_e32 v108, v63
	v_mov_b32_e32 v109, v69
	v_mov_b32_e32 v110, v57
	v_mov_b32_e32 v111, v61
	v_bfe_u32 v55, v100, 16, 1
	v_pk_mul_f32 v[108:109], v[82:83], v[108:109] op_sel_hi:[0,1]
	v_pk_mul_f32 v[110:111], v[82:83], v[110:111] op_sel_hi:[0,1]
	v_add3_u32 v55, v100, v55, s27
	v_bfe_u32 v57, v101, 16, 1
	v_pk_mul_f32 v[96:97], v[96:97], v[110:111]
	v_pk_mul_f32 v[98:99], v[98:99], v[108:109]
	v_lshrrev_b32_e32 v55, 16, v55
; __device__ __forceinline__ unsigned pk2(float lo, float hi) { return f2bf(lo) | (f2bf(hi) << 16); }
; template <bool ZP, bool XF32, bool OUT8 = false>
; __device__ __forceinline__ void norm_phase(LAS unsigned char* lds, const void* xin, const float* gain, const float* sh, const float* sc, bf16* hout, const float* wzt, float* zout, int lane, int wave, int vcu, int G) {
;     ...
;             for (int j = 0; j < 4; ++j) { const int col = 512 * j + 8 * lane;
; #pragma unroll
;                 for (int q = 0; q < 2; ++q) { const f32x4 gg = *(const f32x4*)(gain + col + 4 * q), s1 = *(const f32x4*)(sc + (size_t)b * MODW + col + 4 * q), s0 = *(const f32x4*)(sh + (size_t)b * MODW + col + 4 * q);
;                     v[r][j][q] = (v[r][j][q] * rstd * gg) * (s1 + 1.0f) + s0; }
;                 if constexpr (OUT8) { *(v2u*)((unsigned char*)hout + (size_t)m * D + col) = pack8_fp8(v[r][j][0][0], v[r][j][0][1], v[r][j][0][2], v[r][j][0][3], v[r][j][1][0], v[r][j][1][1], v[r][j][1][2], v[r][j][1][3], FP8_ASCALE); }
;                 else { v4u o; o.x = pk2(v[r][j][0][0], v[r][j][0][1]); o.y = pk2(v[r][j][0][2], v[r][j][0][3]); o.z = pk2(v[r][j][1][0], v[r][j][1][1]); o.w = pk2(v[r][j][1][2], v[r][j][1][3]);
;                     *(v4u*)(hout + (size_t)m * D + col) = o; } }
	v_add3_u32 v57, v101, v57, s27
	v_pk_fma_f32 v[98:99], v[94:95], v[98:99], v[106:107]
	v_pk_fma_f32 v[94:95], v[92:93], v[96:97], v[104:105]
	v_and_or_b32 v92, v57, s25, v55
	v_bfe_u32 v55, v102, 16, 1
	v_add3_u32 v55, v102, v55, s27
	v_bfe_u32 v57, v103, 16, 1
	v_lshrrev_b32_e32 v55, 16, v55
	v_add3_u32 v57, v103, v57, s27
	v_and_or_b32 v93, v57, s25, v55
	v_bfe_u32 v55, v94, 16, 1
	v_add3_u32 v55, v94, v55, s27
	v_bfe_u32 v57, v95, 16, 1
	v_lshrrev_b32_e32 v55, 16, v55
	v_add3_u32 v57, v95, v57, s27
	v_and_or_b32 v94, v57, s25, v55
	v_bfe_u32 v55, v98, 16, 1
	v_add3_u32 v55, v98, v55, s27
	v_bfe_u32 v57, v99, 16, 1
	v_lshrrev_b32_e32 v55, 16, v55
	v_add3_u32 v57, v99, v57, s27
	v_and_or_b32 v95, v57, s25, v55
	global_store_dwordx4 v[80:81], v[92:95], off
	s_nop 1
	v_mov_b64_e32 v[92:93], v[152:153]
	v_mov_b64_e32 v[94:95], v[154:155]
	s_nop 0
	s_nop 1
	v_mov_b64_e32 v[96:97], v[156:157]
	v_mov_b64_e32 v[98:99], v[158:159]
	v_mov_b64_e32 v[100:101], v[160:161]
	v_mov_b64_e32 v[102:103], v[162:163]
	v_mov_b64_e32 v[104:105], v[164:165]
	v_mov_b64_e32 v[106:107], v[166:167]
	v_mov_b64_e32 v[108:109], v[168:169]
	v_mov_b64_e32 v[110:111], v[170:171]
	v_mov_b64_e32 v[112:113], v[172:173]
	v_mov_b64_e32 v[114:115], v[174:175]
	v_mov_b32_e32 v118, v43
	v_mov_b32_e32 v119, v27
	v_pk_mul_f32 v[118:119], v[82:83], v[118:119] op_sel_hi:[0,1]
	v_mov_b32_e32 v116, v47
	v_mov_b32_e32 v117, v49
	v_pk_mul_f32 v[116:117], v[82:83], v[116:117] op_sel_hi:[0,1]
	v_mov_b32_e32 v63, v68
	v_mov_b32_e32 v57, v60
	v_mov_b32_e32 v55, v58
	v_mov_b32_e32 v47, v48
	v_mov_b32_e32 v43, v26
	v_pk_mov_b32 v[2:3], v[2:3], v[2:3] op_sel:[1,0]
	v_pk_mov_b32 v[4:5], v[4:5], v[4:5] op_sel:[1,0]
	s_add_i32 s24, s24, 1
	s_addk_i32 s23, 0x200
	s_add_i32 s3, s3, -1
	s_cmp_eq_u32 s3, 0
	v_pk_mul_f32 v[92:93], v[92:93], v[118:119]
	v_pk_add_f32 v[96:97], v[96:97], 1.0 op_sel_hi:[1,0]
	v_pk_mul_f32 v[94:95], v[94:95], v[116:117]
	v_pk_fma_f32 v[92:93], v[96:97], v[92:93], v[100:101]
	v_pk_add_f32 v[98:99], v[98:99], 1.0 op_sel_hi:[1,0]
	v_bfe_u32 v27, v92, 16, 1
	v_pk_fma_f32 v[94:95], v[98:99], v[94:95], v[102:103]
	v_mov_b32_e32 v99, v31
	v_add3_u32 v27, v92, v27, s27
	v_bfe_u32 v31, v93, 16, 1
	v_mov_b32_e32 v98, v45
	v_lshrrev_b32_e32 v27, 16, v27
	v_add3_u32 v31, v93, v31, s27
	v_pk_mul_f32 v[98:99], v[82:83], v[98:99] op_sel_hi:[0,1]
	v_and_or_b32 v92, v31, s25, v27
	v_bfe_u32 v27, v94, 16, 1
	v_pk_mul_f32 v[98:99], v[104:105], v[98:99]
	v_pk_add_f32 v[102:103], v[108:109], 1.0 op_sel_hi:[1,0]
	v_add3_u32 v27, v94, v27, s27
	v_bfe_u32 v31, v95, 16, 1
	v_mov_b32_e32 v96, v51
	v_mov_b32_e32 v97, v53
	v_pk_fma_f32 v[98:99], v[102:103], v[98:99], v[112:113]
	v_lshrrev_b32_e32 v27, 16, v27
	v_add3_u32 v31, v95, v31, s27
	v_pk_mul_f32 v[96:97], v[82:83], v[96:97] op_sel_hi:[0,1]
	v_and_or_b32 v93, v31, s25, v27
	v_bfe_u32 v27, v98, 16, 1
	v_pk_mul_f32 v[96:97], v[106:107], v[96:97]
	v_pk_add_f32 v[100:101], v[110:111], 1.0 op_sel_hi:[1,0]
	v_add3_u32 v27, v98, v27, s27
	v_bfe_u32 v31, v99, 16, 1
	v_pk_fma_f32 v[96:97], v[100:101], v[96:97], v[114:115]
	v_lshrrev_b32_e32 v27, 16, v27
	v_add3_u32 v31, v99, v31, s27
	v_and_or_b32 v94, v31, s25, v27
	v_bfe_u32 v27, v96, 16, 1
	v_add3_u32 v27, v96, v27, s27
	v_bfe_u32 v31, v97, 16, 1
	v_lshrrev_b32_e32 v27, 16, v27
	v_add3_u32 v31, v97, v31, s27
	v_and_or_b32 v95, v31, s25, v27
	global_store_dwordx4 v[80:81], v[92:95], off offset:1024
	s_nop 1
	v_mov_b64_e32 v[92:93], v[176:177]
	v_mov_b64_e32 v[94:95], v[178:179]
	s_nop 0
	s_nop 1
	v_mov_b64_e32 v[96:97], v[180:181]
	v_mov_b64_e32 v[98:99], v[182:183]
	v_mov_b64_e32 v[100:101], v[184:185]
	v_mov_b64_e32 v[102:103], v[186:187]
	v_mov_b64_e32 v[104:105], v[188:189]
	v_mov_b64_e32 v[106:107], v[190:191]
	v_mov_b64_e32 v[108:109], v[192:193]
	v_mov_b64_e32 v[110:111], v[194:195]
	v_mov_b64_e32 v[112:113], v[196:197]
	v_mov_b64_e32 v[114:115], v[198:199]
	v_mov_b32_e32 v118, v23
	v_mov_b32_e32 v119, v25
	v_pk_mul_f32 v[118:119], v[82:83], v[118:119] op_sel_hi:[0,1]
	v_mov_b32_e32 v116, v29
	v_mov_b32_e32 v117, v33
	v_pk_mul_f32 v[116:117], v[82:83], v[116:117] op_sel_hi:[0,1]
	v_mov_b32_e32 v51, v52
	v_mov_b32_e32 v45, v30
	v_pk_mul_f32 v[92:93], v[92:93], v[118:119]
	v_pk_add_f32 v[96:97], v[96:97], 1.0 op_sel_hi:[1,0]
	v_pk_mul_f32 v[94:95], v[94:95], v[116:117]
	v_pk_add_f32 v[98:99], v[98:99], 1.0 op_sel_hi:[1,0]
	v_pk_fma_f32 v[92:93], v[96:97], v[92:93], v[108:109]
	v_pk_fma_f32 v[94:95], v[98:99], v[94:95], v[110:111]
	v_bfe_u32 v23, v92, 16, 1
	v_bfe_u32 v25, v93, 16, 1
	v_add3_u32 v23, v92, v23, s27
	v_lshrrev_b32_e32 v23, 16, v23
	v_add3_u32 v25, v93, v25, s27
	v_and_or_b32 v92, v25, s25, v23
	v_bfe_u32 v23, v94, 16, 1
	v_pk_mul_f32 v[100:101], v[100:101], v[122:123]
	v_pk_add_f32 v[104:105], v[104:105], 1.0 op_sel_hi:[1,0]
	v_add3_u32 v23, v94, v23, s27
	v_bfe_u32 v25, v95, 16, 1
	v_pk_fma_f32 v[98:99], v[104:105], v[100:101], v[112:113]
	v_lshrrev_b32_e32 v23, 16, v23
	v_add3_u32 v25, v95, v25, s27
	v_and_or_b32 v93, v25, s25, v23
	v_bfe_u32 v23, v98, 16, 1
	v_pk_mul_f32 v[102:103], v[102:103], v[120:121]
	v_pk_add_f32 v[106:107], v[106:107], 1.0 op_sel_hi:[1,0]
	v_add3_u32 v23, v98, v23, s27
	v_bfe_u32 v25, v99, 16, 1
	v_pk_fma_f32 v[96:97], v[106:107], v[102:103], v[114:115]
	v_lshrrev_b32_e32 v23, 16, v23
	v_add3_u32 v25, v99, v25, s27
	v_and_or_b32 v94, v25, s25, v23
	v_bfe_u32 v23, v96, 16, 1
	v_add3_u32 v23, v96, v23, s27
	v_bfe_u32 v25, v97, 16, 1
	v_lshrrev_b32_e32 v23, 16, v23
	v_add3_u32 v25, v97, v25, s27
	v_and_or_b32 v95, v25, s25, v23
	global_store_dwordx4 v[80:81], v[92:95], off offset:2048
	s_nop 1
	v_mov_b64_e32 v[92:93], v[200:201]
	v_mov_b64_e32 v[94:95], v[202:203]
; __device__ __forceinline__ unsigned pk2(float lo, float hi) { return f2bf(lo) | (f2bf(hi) << 16); }
; template <bool ZP, bool XF32, bool OUT8 = false>
; __device__ __forceinline__ void norm_phase(LAS unsigned char* lds, const void* xin, const float* gain, const float* sh, const float* sc, bf16* hout, const float* wzt, float* zout, int lane, int wave, int vcu, int G) {
;     ...
;         for (int r = 0; r < 2; ++r) { const int m = m0 + r, b = m >> 11;
;             const float rstd = rsqrtf(wave_sum(ss[r]) * (1.0f / D) + EPS);
; #pragma unroll
;             for (int j = 0; j < 4; ++j) { const int col = 512 * j + 8 * lane;
; #pragma unroll
;                 for (int q = 0; q < 2; ++q) { const f32x4 gg = *(const f32x4*)(gain + col + 4 * q), s1 = *(const f32x4*)(sc + (size_t)b * MODW + col + 4 * q), s0 = *(const f32x4*)(sh + (size_t)b * MODW + col + 4 * q);
;                     v[r][j][q] = (v[r][j][q] * rstd * gg) * (s1 + 1.0f) + s0; }
;                 if constexpr (OUT8) { *(v2u*)((unsigned char*)hout + (size_t)m * D + col) = pack8_fp8(v[r][j][0][0], v[r][j][0][1], v[r][j][0][2], v[r][j][0][3], v[r][j][1][0], v[r][j][1][1], v[r][j][1][2], v[r][j][1][3], FP8_ASCALE); }
;                 else { v4u o; o.x = pk2(v[r][j][0][0], v[r][j][0][1]); o.y = pk2(v[r][j][0][2], v[r][j][0][3]); o.z = pk2(v[r][j][1][0], v[r][j][1][1]); o.w = pk2(v[r][j][1][2], v[r][j][1][3]);
;                     *(v4u*)(hout + (size_t)m * D + col) = o; } }
	s_nop 0
	s_nop 1
	v_mov_b64_e32 v[96:97], v[204:205]
	v_mov_b64_e32 v[98:99], v[206:207]
	v_mov_b64_e32 v[100:101], v[208:209]
	v_mov_b64_e32 v[102:103], v[210:211]
	v_mov_b64_e32 v[104:105], v[212:213]
	v_mov_b64_e32 v[106:107], v[214:215]
	v_mov_b64_e32 v[108:109], v[216:217]
	v_mov_b64_e32 v[110:111], v[218:219]
	v_mov_b64_e32 v[112:113], v[220:221]
	v_mov_b64_e32 v[114:115], v[222:223]
	v_mov_b32_e32 v116, v71
	v_mov_b32_e32 v117, v70
	v_mov_b32_e32 v70, v73
	v_mov_b32_e32 v71, v72
	v_pk_mul_f32 v[72:73], v[82:83], v[74:75] op_sel_hi:[0,1]
	v_pk_mul_f32 v[74:75], v[82:83], v[116:117] op_sel_hi:[0,1]
	v_pk_mul_f32 v[70:71], v[82:83], v[70:71] op_sel_hi:[0,1]
	v_pk_mul_f32 v[74:75], v[74:75], v[92:93]
	v_pk_mul_f32 v[72:73], v[72:73], v[94:95]
	v_pk_add_f32 v[92:93], v[98:99], 1.0 op_sel_hi:[1,0]
	v_pk_add_f32 v[94:95], v[96:97], 1.0 op_sel_hi:[1,0]
	v_pk_mul_f32 v[70:71], v[70:71], v[100:101]
	v_pk_mul_f32 v[76:77], v[76:77], v[102:103]
	v_pk_add_f32 v[96:97], v[106:107], 1.0 op_sel_hi:[1,0]
	v_pk_add_f32 v[98:99], v[104:105], 1.0 op_sel_hi:[1,0]
	v_pk_fma_f32 v[72:73], v[72:73], v[92:93], v[110:111]
	v_pk_fma_f32 v[74:75], v[74:75], v[94:95], v[108:109]
	v_pk_fma_f32 v[76:77], v[76:77], v[96:97], v[114:115]
	v_pk_fma_f32 v[70:71], v[70:71], v[98:99], v[112:113]
	v_bfe_u32 v23, v74, 16, 1
	v_bfe_u32 v27, v72, 16, 1
	v_bfe_u32 v31, v70, 16, 1
	v_bfe_u32 v35, v76, 16, 1
	v_bfe_u32 v25, v75, 16, 1
	v_bfe_u32 v29, v73, 16, 1
	v_bfe_u32 v33, v71, 16, 1
	v_bfe_u32 v37, v77, 16, 1
	v_add3_u32 v23, v74, v23, s27
	v_add3_u32 v27, v72, v27, s27
	v_add3_u32 v31, v70, v31, s27
	v_add3_u32 v35, v76, v35, s27
	v_add3_u32 v25, v75, v25, s27
	v_add3_u32 v29, v73, v29, s27
	v_add3_u32 v33, v71, v33, s27
	v_add3_u32 v37, v77, v37, s27
	v_lshrrev_b32_e32 v23, 16, v23
	v_lshrrev_b32_e32 v27, 16, v27
	v_lshrrev_b32_e32 v31, 16, v31
	v_lshrrev_b32_e32 v35, 16, v35
	v_and_or_b32 v70, v25, s25, v23
	v_and_or_b32 v71, v29, s25, v27
	v_and_or_b32 v72, v33, s25, v31
	v_and_or_b32 v73, v37, s25, v35
	global_store_dwordx4 v[80:81], v[70:73], off offset:3072
	s_nop 1
	v_mov_b64_e32 v[72:73], v[140:141]
	v_mov_b64_e32 v[74:75], v[142:143]
	s_nop 0
	s_nop 1
	v_mov_b64_e32 v[92:93], v[132:133]
	v_mov_b64_e32 v[94:95], v[134:135]
	v_mov_b64_e32 v[96:97], v[136:137]
	v_mov_b64_e32 v[98:99], v[138:139]
	v_mov_b64_e32 v[100:101], v[128:129]
	v_mov_b64_e32 v[102:103], v[130:131]
	v_mov_b64_e32 v[104:105], v[148:149]
	v_mov_b64_e32 v[106:107], v[150:151]
	v_mov_b64_e32 v[108:109], v[144:145]
	v_mov_b64_e32 v[110:111], v[146:147]
	v_mul_f32_e32 v23, 0x4b800000, v78
	v_cndmask_b32_e32 v23, v78, v23, vcc
	v_rsq_f32_e32 v23, v23
	v_lshl_add_u64 v[70:71], v[14:15], 0, s[8:9]
	s_cselect_b64 s[8:9], -1, 0
	v_mul_f32_e32 v25, 0x45800000, v23
	v_cndmask_b32_e32 v58, v23, v25, vcc
	v_pk_mul_f32 v[60:61], v[58:59], v[64:65] op_sel_hi:[0,1]
	v_pk_mul_f32 v[54:55], v[58:59], v[54:55] op_sel_hi:[0,1]
	v_pk_mul_f32 v[62:63], v[58:59], v[62:63] op_sel_hi:[0,1]
	v_pk_mul_f32 v[56:57], v[58:59], v[56:57] op_sel_hi:[0,1]
	v_pk_mul_f32 v[44:45], v[58:59], v[44:45] op_sel_hi:[0,1]
	v_pk_mul_f32 v[2:3], v[58:59], v[2:3] op_sel_hi:[0,1]
	v_pk_mul_f32 v[4:5], v[58:59], v[4:5] op_sel_hi:[0,1]
	v_pk_add_f32 v[64:65], v[94:95], 1.0 op_sel_hi:[1,0]
	v_pk_mul_f32 v[54:55], v[72:73], v[54:55]
	v_pk_mul_f32 v[60:61], v[74:75], v[60:61]
	v_pk_add_f32 v[66:67], v[92:93], 1.0 op_sel_hi:[1,0]
	v_pk_mul_f32 v[56:57], v[96:97], v[56:57]
	v_pk_mul_f32 v[62:63], v[98:99], v[62:63]
	v_pk_add_f32 v[68:69], v[102:103], 1.0 op_sel_hi:[1,0]
	v_pk_add_f32 v[72:73], v[100:101], 1.0 op_sel_hi:[1,0]
	v_pk_fma_f32 v[60:61], v[64:65], v[60:61], v[106:107]
	v_pk_fma_f32 v[54:55], v[66:67], v[54:55], v[104:105]
	v_pk_fma_f32 v[62:63], v[68:69], v[62:63], v[110:111]
	v_pk_fma_f32 v[56:57], v[72:73], v[56:57], v[108:109]
	v_bfe_u32 v23, v54, 16, 1
	v_bfe_u32 v27, v60, 16, 1
	v_bfe_u32 v31, v56, 16, 1
	v_bfe_u32 v35, v62, 16, 1
	v_bfe_u32 v25, v55, 16, 1
	v_bfe_u32 v29, v61, 16, 1
	v_bfe_u32 v33, v57, 16, 1
	v_bfe_u32 v37, v63, 16, 1
	v_add3_u32 v23, v54, v23, s27
	v_add3_u32 v27, v60, v27, s27
	v_add3_u32 v31, v56, v31, s27
	v_add3_u32 v35, v62, v35, s27
	v_add3_u32 v25, v55, v25, s27
	v_add3_u32 v29, v61, v29, s27
	v_add3_u32 v33, v57, v33, s27
	v_add3_u32 v37, v63, v37, s27
	v_lshrrev_b32_e32 v23, 16, v23
	v_lshrrev_b32_e32 v27, 16, v27
	v_lshrrev_b32_e32 v31, 16, v31
	v_lshrrev_b32_e32 v35, 16, v35
	v_and_or_b32 v54, v25, s25, v23
	v_and_or_b32 v55, v29, s25, v27
	v_and_or_b32 v56, v33, s25, v31
	v_and_or_b32 v57, v37, s25, v35
	global_store_dwordx4 v[70:71], v[54:57], off
	s_nop 1
	v_mov_b64_e32 v[54:55], v[152:153]
	v_mov_b64_e32 v[56:57], v[154:155]
	s_nop 0
	s_nop 1
	v_mov_b64_e32 v[60:61], v[156:157]
	v_mov_b64_e32 v[62:63], v[158:159]
	v_mov_b64_e32 v[64:65], v[164:165]
	v_mov_b64_e32 v[66:67], v[166:167]
	v_mov_b64_e32 v[72:73], v[168:169]
	v_mov_b64_e32 v[74:75], v[170:171]
	v_mov_b64_e32 v[76:77], v[160:161]
	v_mov_b64_e32 v[78:79], v[162:163]
	v_mov_b64_e32 v[92:93], v[172:173]
	v_mov_b64_e32 v[94:95], v[174:175]
	v_pk_mul_f32 v[26:27], v[58:59], v[46:47] op_sel_hi:[0,1]
	v_pk_mul_f32 v[30:31], v[58:59], v[42:43] op_sel_hi:[0,1]
	v_pk_mul_f32 v[42:43], v[58:59], v[50:51] op_sel_hi:[0,1]
	v_pk_mul_f32 v[30:31], v[54:55], v[30:31]
	v_pk_mul_f32 v[26:27], v[56:57], v[26:27]
	v_pk_add_f32 v[46:47], v[62:63], 1.0 op_sel_hi:[1,0]
	v_pk_add_f32 v[48:49], v[60:61], 1.0 op_sel_hi:[1,0]
; __device__ __forceinline__ unsigned pk2(float lo, float hi) { return f2bf(lo) | (f2bf(hi) << 16); }
; template <bool ZP, bool XF32, bool OUT8 = false>
; __device__ __forceinline__ void norm_phase(LAS unsigned char* lds, const void* xin, const float* gain, const float* sh, const float* sc, bf16* hout, const float* wzt, float* zout, int lane, int wave, int vcu, int G) {
;     ...
;             for (int j = 0; j < 4; ++j) { const int col = 512 * j + 8 * lane;
; #pragma unroll
;                 for (int q = 0; q < 2; ++q) { const f32x4 gg = *(const f32x4*)(gain + col + 4 * q), s1 = *(const f32x4*)(sc + (size_t)b * MODW + col + 4 * q), s0 = *(const f32x4*)(sh + (size_t)b * MODW + col + 4 * q);
;                     v[r][j][q] = (v[r][j][q] * rstd * gg) * (s1 + 1.0f) + s0; }
;                 if constexpr (OUT8) { *(v2u*)((unsigned char*)hout + (size_t)m * D + col) = pack8_fp8(v[r][j][0][0], v[r][j][0][1], v[r][j][0][2], v[r][j][0][3], v[r][j][1][0], v[r][j][1][1], v[r][j][1][2], v[r][j][1][3], FP8_ASCALE); }
;                 else { v4u o; o.x = pk2(v[r][j][0][0], v[r][j][0][1]); o.y = pk2(v[r][j][0][2], v[r][j][0][3]); o.z = pk2(v[r][j][1][0], v[r][j][1][1]); o.w = pk2(v[r][j][1][2], v[r][j][1][3]);
;                     *(v4u*)(hout + (size_t)m * D + col) = o; } }
	v_pk_mul_f32 v[44:45], v[64:65], v[44:45]
	v_pk_mul_f32 v[42:43], v[66:67], v[42:43]
	v_pk_add_f32 v[50:51], v[74:75], 1.0 op_sel_hi:[1,0]
	v_pk_add_f32 v[52:53], v[72:73], 1.0 op_sel_hi:[1,0]
	v_pk_fma_f32 v[26:27], v[46:47], v[26:27], v[78:79]
	v_pk_fma_f32 v[30:31], v[48:49], v[30:31], v[76:77]
	v_pk_fma_f32 v[42:43], v[50:51], v[42:43], v[94:95]
	v_pk_fma_f32 v[44:45], v[52:53], v[44:45], v[92:93]
	v_bfe_u32 v23, v30, 16, 1
	v_bfe_u32 v25, v31, 16, 1
	v_bfe_u32 v29, v26, 16, 1
	v_bfe_u32 v35, v44, 16, 1
	v_bfe_u32 v39, v42, 16, 1
	v_bfe_u32 v33, v27, 16, 1
	v_bfe_u32 v37, v45, 16, 1
	v_bfe_u32 v41, v43, 16, 1
	v_add3_u32 v23, v30, v23, s27
	v_add3_u32 v25, v31, v25, s27
	v_add3_u32 v26, v26, v29, s27
	v_add3_u32 v29, v44, v35, s27
	v_add3_u32 v31, v42, v39, s27
	v_add3_u32 v27, v27, v33, s27
	v_add3_u32 v30, v45, v37, s27
	v_add3_u32 v33, v43, v41, s27
	v_lshrrev_b32_e32 v23, 16, v23
	v_lshrrev_b32_e32 v26, 16, v26
	v_lshrrev_b32_e32 v29, 16, v29
	v_lshrrev_b32_e32 v31, 16, v31
	v_and_or_b32 v42, v25, s25, v23
	v_and_or_b32 v43, v27, s25, v26
	v_and_or_b32 v44, v30, s25, v29
	v_and_or_b32 v45, v33, s25, v31
	global_store_dwordx4 v[70:71], v[42:45], off offset:1024
	s_nop 1
	v_mov_b64_e32 v[42:43], v[176:177]
	v_mov_b64_e32 v[44:45], v[178:179]
	s_nop 0
	s_nop 1
	v_mov_b64_e32 v[46:47], v[180:181]
	v_mov_b64_e32 v[48:49], v[182:183]
	v_mov_b64_e32 v[50:51], v[184:185]
	v_mov_b64_e32 v[52:53], v[186:187]
	v_mov_b64_e32 v[54:55], v[188:189]
	v_mov_b64_e32 v[56:57], v[190:191]
	v_mov_b64_e32 v[60:61], v[192:193]
	v_mov_b64_e32 v[62:63], v[194:195]
	v_mov_b64_e32 v[64:65], v[196:197]
	v_mov_b64_e32 v[66:67], v[198:199]
	v_mov_b32_e32 v39, v40
	v_mov_b32_e32 v35, v36
	v_mov_b32_e32 v29, v32
	v_mov_b32_e32 v23, v24
	v_pk_mul_f32 v[24:25], v[58:59], v[28:29] op_sel_hi:[0,1]
	v_pk_mul_f32 v[22:23], v[58:59], v[22:23] op_sel_hi:[0,1]
	v_pk_mul_f32 v[26:27], v[58:59], v[38:39] op_sel_hi:[0,1]
	v_pk_mul_f32 v[28:29], v[58:59], v[34:35] op_sel_hi:[0,1]
	v_pk_mul_f32 v[22:23], v[22:23], v[42:43]
	v_pk_mul_f32 v[24:25], v[24:25], v[44:45]
	v_pk_add_f32 v[30:31], v[48:49], 1.0 op_sel_hi:[1,0]
	v_pk_add_f32 v[32:33], v[46:47], 1.0 op_sel_hi:[1,0]
	v_pk_mul_f32 v[28:29], v[28:29], v[50:51]
	v_pk_mul_f32 v[26:27], v[26:27], v[52:53]
	v_pk_add_f32 v[34:35], v[56:57], 1.0 op_sel_hi:[1,0]
	v_pk_add_f32 v[36:37], v[54:55], 1.0 op_sel_hi:[1,0]
	v_pk_fma_f32 v[24:25], v[24:25], v[30:31], v[62:63]
	v_pk_fma_f32 v[22:23], v[22:23], v[32:33], v[60:61]
	v_pk_fma_f32 v[26:27], v[26:27], v[34:35], v[66:67]
	v_pk_fma_f32 v[28:29], v[28:29], v[36:37], v[64:65]
	v_bfe_u32 v30, v22, 16, 1
	v_bfe_u32 v32, v24, 16, 1
	v_bfe_u32 v34, v28, 16, 1
	v_bfe_u32 v36, v26, 16, 1
	v_bfe_u32 v31, v23, 16, 1
	v_bfe_u32 v33, v25, 16, 1
	v_bfe_u32 v35, v29, 16, 1
	v_bfe_u32 v37, v27, 16, 1
	v_add3_u32 v22, v22, v30, s27
	v_add3_u32 v24, v24, v32, s27
	v_add3_u32 v28, v28, v34, s27
	v_add3_u32 v26, v26, v36, s27
	v_add3_u32 v23, v23, v31, s27
	v_add3_u32 v25, v25, v33, s27
	v_add3_u32 v29, v29, v35, s27
	v_add3_u32 v27, v27, v37, s27
	v_lshrrev_b32_e32 v22, 16, v22
	v_lshrrev_b32_e32 v24, 16, v24
	v_lshrrev_b32_e32 v28, 16, v28
	v_lshrrev_b32_e32 v26, 16, v26
	v_and_or_b32 v22, v23, s25, v22
	v_and_or_b32 v23, v25, s25, v24
	v_and_or_b32 v24, v29, s25, v28
	v_and_or_b32 v25, v27, s25, v26
	global_store_dwordx4 v[70:71], v[22:25], off offset:2048
	s_nop 1
	v_mov_b64_e32 v[22:23], v[200:201]
	v_mov_b64_e32 v[24:25], v[202:203]
	s_nop 0
	s_nop 1
	v_mov_b64_e32 v[26:27], v[204:205]
	v_mov_b64_e32 v[28:29], v[206:207]
	v_mov_b64_e32 v[30:31], v[208:209]
	v_mov_b64_e32 v[32:33], v[210:211]
	v_mov_b64_e32 v[34:35], v[212:213]
	v_mov_b64_e32 v[36:37], v[214:215]
	v_mov_b64_e32 v[38:39], v[216:217]
	v_mov_b64_e32 v[40:41], v[218:219]
	v_mov_b64_e32 v[42:43], v[220:221]
	v_mov_b64_e32 v[44:45], v[222:223]
	v_mov_b32_e32 v46, v21
	v_mov_b32_e32 v47, v20
	v_mov_b32_e32 v20, v19
	v_mov_b32_e32 v21, v18
	v_pk_mul_f32 v[18:19], v[58:59], v[46:47] op_sel_hi:[0,1]
	v_pk_mul_f32 v[20:21], v[58:59], v[20:21] op_sel_hi:[0,1]
	v_pk_mul_f32 v[18:19], v[18:19], v[22:23]
	v_pk_mul_f32 v[2:3], v[2:3], v[24:25]
	v_pk_add_f32 v[22:23], v[28:29], 1.0 op_sel_hi:[1,0]
	v_pk_add_f32 v[24:25], v[26:27], 1.0 op_sel_hi:[1,0]
	v_pk_mul_f32 v[20:21], v[20:21], v[30:31]
	v_pk_mul_f32 v[4:5], v[4:5], v[32:33]
	v_pk_add_f32 v[26:27], v[36:37], 1.0 op_sel_hi:[1,0]
	v_pk_add_f32 v[28:29], v[34:35], 1.0 op_sel_hi:[1,0]
	v_pk_fma_f32 v[2:3], v[2:3], v[22:23], v[40:41]
	v_pk_fma_f32 v[18:19], v[18:19], v[24:25], v[38:39]
	v_pk_fma_f32 v[4:5], v[4:5], v[26:27], v[44:45]
	v_pk_fma_f32 v[20:21], v[20:21], v[28:29], v[42:43]
	v_bfe_u32 v22, v18, 16, 1
	v_bfe_u32 v24, v2, 16, 1
	v_bfe_u32 v26, v20, 16, 1
	v_bfe_u32 v28, v4, 16, 1
	v_bfe_u32 v23, v19, 16, 1
	v_bfe_u32 v25, v3, 16, 1
	v_bfe_u32 v27, v21, 16, 1
	v_bfe_u32 v29, v5, 16, 1
	v_add3_u32 v18, v18, v22, s27
	v_add3_u32 v2, v2, v24, s27
	v_add3_u32 v20, v20, v26, s27
	v_add3_u32 v4, v4, v28, s27
	v_add3_u32 v19, v19, v23, s27
	v_add3_u32 v3, v3, v25, s27
	v_add3_u32 v21, v21, v27, s27
	v_add3_u32 v5, v5, v29, s27
	v_lshrrev_b32_e32 v18, 16, v18
	v_lshrrev_b32_e32 v22, 16, v2
	v_lshrrev_b32_e32 v20, 16, v20
	v_lshrrev_b32_e32 v23, 16, v4
	v_and_or_b32 v2, v19, s25, v18
	v_and_or_b32 v3, v3, s25, v22
	v_and_or_b32 v4, v21, s25, v20
	v_and_or_b32 v5, v5, s25, v23
	global_store_dwordx4 v[70:71], v[2:5], off offset:3072
	s_branch .LBB0_678

; __device__ __forceinline__ void unpack8(const v4u& w, float (&f)[8]) { f[0] = bflo(w.x); f[1] = bfhi(w.x); f[2] = bflo(w.y); f[3] = bfhi(w.y); f[4] = bflo(w.z); f[5] = bfhi(w.z); f[6] = bflo(w.w); f[7] = bfhi(w.w); }
; template <bool ZP, bool XF32, bool OUT8 = false>
; __device__ __forceinline__ void norm_phase(LAS unsigned char* lds, const void* xin, const float* gain, const float* sh, const float* sc, bf16* hout, const float* wzt, float* zout, int lane, int wave, int vcu, int G) {
;     ...
;     for (int it_ = 0; it_ < nit; ++it_) {
;         const int m0 = xdeal ? 2048 * (gw >> 8) + 2 * (gw & 255) + 512 * it_ : 2 * gw + it_ * 2 * NGW;
;         if (m0 >= M) break;
;         f32x4 v[2][4][2]; float ss[2] = {0.f, 0.f};
; #pragma unroll
;         for (int r = 0; r < 2; ++r)
; #pragma unroll
;             for (int j = 0; j < 4; ++j) {
;                 if constexpr (XF32) { const float* xr = (const float*)xin + (size_t)(m0 + r) * D + 8 * lane; v[r][j][0] = *(const f32x4*)(xr + 512 * j); v[r][j][1] = *(const f32x4*)(xr + 512 * j + 4); }
;                 else { float f[8]; unpack8(*(const v4u*)((const bf16*)xin + (size_t)(m0 + r) * D + 8 * lane + 512 * j), f); v[r][j][0] = (f32x4){f[0], f[1], f[2], f[3]}; v[r][j][1] = (f32x4){f[4], f[5], f[6], f[7]}; } }
; #pragma unroll
;         for (int r = 0; r < 2; ++r)
; #pragma unroll
;             for (int j = 0; j < 4; ++j)
; #pragma unroll
;                 for (int e = 0; e < 4; ++e) ss[r] += v[r][j][0][e] * v[r][j][0][e] + v[r][j][1][e] * v[r][j][1][e];
; #pragma unroll
;         for (int r = 0; r < 2; ++r) { const int m = m0 + r, b = m >> 11;
;             const float rstd = rsqrtf(wave_sum(ss[r]) * (1.0f / D) + EPS);
; #pragma unroll
;             for (int j = 0; j < 4; ++j) { const int col = 512 * j + 8 * lane;
; #pragma unroll
;                 for (int q = 0; q < 2; ++q) { const f32x4 gg = *(const f32x4*)(gain + col + 4 * q), s1 = *(const f32x4*)(sc + (size_t)b * MODW + col + 4 * q), s0 = *(const f32x4*)(sh + (size_t)b * MODW + col + 4 * q);
;                     v[r][j][q] = (v[r][j][q] * rstd * gg) * (s1 + 1.0f) + s0; }
.LBB0_940:
	s_ashr_i32 s15, s14, 31
	s_add_i32 s10, s14, 1
	s_lshl_b64 s[12:13], s[14:15], 12
	s_ashr_i32 s11, s10, 31
	v_lshl_add_u64 v[2:3], v[6:7], 0, s[12:13]
	v_lshl_add_u64 v[244:245], v[2:3], 0, s[100:101]
	s_lshl_b64 s[8:9], s[10:11], 12
	global_load_dwordx4 v[20:23], v[2:3], off offset:1024
	global_load_dwordx4 v[24:27], v[2:3], off offset:3072
	global_load_dwordx4 v[34:37], v[2:3], off
	global_load_dwordx4 v[40:43], v[2:3], off offset:2048
	v_lshl_add_u64 v[28:29], v[6:7], 0, s[8:9]
	v_lshl_add_u64 v[246:247], v[28:29], 0, s[100:101]
	global_load_dwordx4 v[80:83], v[28:29], off offset:1024
	global_load_dwordx4 v[94:97], v[28:29], off
	global_load_dwordx4 v[2:5], v[28:29], off offset:3072
	global_load_dwordx4 v[98:101], v[28:29], off offset:2048
	s_ashr_i32 s0, s14, 11
	s_mul_hi_i32 s1, s0, 0xc000
	s_mul_i32 s0, s0, 0xc000
	s_add_u32 s14, s19, s0
	s_addc_u32 s15, s20, s1
	s_add_u32 s16, s7, s0
	s_addc_u32 s17, s18, s1
	v_cmp_lt_i32_e32 vcc, v88, v87
	s_ashr_i32 s0, s10, 11
	s_mul_hi_i32 s1, s0, 0xc000
	v_cndmask_b32_e32 v84, v86, v88, vcc
	v_lshlrev_b32_e32 v84, 2, v84
	v_cmp_lt_i32_e32 vcc, v89, v87
	s_mul_i32 s0, s0, 0xc000
	s_add_u32 s10, s19, s0
	s_addc_u32 s11, s20, s1
	s_waitcnt vmcnt(0)
	v_lshlrev_b32_e32 v47, 16, v22
	v_lshlrev_b32_e32 v45, 16, v20
	v_lshlrev_b32_e32 v59, 16, v36
	v_and_b32_e32 v63, 0xffff0000, v36
	v_lshlrev_b32_e32 v58, 16, v96
	v_and_b32_e32 v62, 0xffff0000, v96
	v_lshlrev_b32_e32 v57, 16, v34
	v_and_b32_e32 v61, 0xffff0000, v34
	v_lshlrev_b32_e32 v65, 16, v37
	v_and_b32_e32 v28, 0xffff0000, v80
	v_and_b32_e32 v32, 0xffff0000, v82
	v_lshlrev_b32_e32 v56, 16, v94
	v_and_b32_e32 v60, 0xffff0000, v94
	v_lshlrev_b32_e32 v64, 16, v97
	v_lshlrev_b32_e32 v44, 16, v80
	v_lshlrev_b32_e32 v46, 16, v82
	v_lshlrev_b32_e32 v48, 16, v81
	v_and_b32_e32 v50, 0xffff0000, v81
	v_lshlrev_b32_e32 v52, 16, v83
	v_and_b32_e32 v54, 0xffff0000, v83
	v_pk_mul_f32 v[80:81], v[58:59], v[58:59]
	v_pk_mul_f32 v[82:83], v[62:63], v[62:63]
	v_lshlrev_b32_e32 v67, 16, v35
	v_and_b32_e32 v71, 0xffff0000, v37
	v_lshlrev_b32_e32 v66, 16, v95
	v_and_b32_e32 v68, 0xffff0000, v95
	v_and_b32_e32 v70, 0xffff0000, v97
	v_pk_mul_f32 v[94:95], v[64:65], v[64:65]
	v_pk_fma_f32 v[80:81], v[56:57], v[56:57], v[80:81]
	v_pk_fma_f32 v[82:83], v[60:61], v[60:61], v[82:83]
	v_and_b32_e32 v69, 0xffff0000, v35
	v_pk_mul_f32 v[96:97], v[70:71], v[70:71]
	v_pk_fma_f32 v[94:95], v[66:67], v[66:67], v[94:95]
	v_pk_add_f32 v[80:81], v[80:81], v[82:83]
	v_pk_fma_f32 v[82:83], v[68:69], v[68:69], v[96:97]
	v_pk_add_f32 v[80:81], v[94:95], v[80:81]
	v_and_b32_e32 v33, 0xffff0000, v22
	v_pk_add_f32 v[80:81], v[82:83], v[80:81]
	v_pk_mul_f32 v[82:83], v[46:47], v[46:47]
	v_and_b32_e32 v29, 0xffff0000, v20
	v_pk_fma_f32 v[82:83], v[44:45], v[44:45], v[82:83]
	v_lshlrev_b32_e32 v53, 16, v23
	v_pk_add_f32 v[80:81], v[82:83], v[80:81]
	v_pk_mul_f32 v[82:83], v[32:33], v[32:33]
	v_lshlrev_b32_e32 v49, 16, v21
	v_pk_fma_f32 v[82:83], v[28:29], v[28:29], v[82:83]
	v_and_b32_e32 v51, 0xffff0000, v21
	v_and_b32_e32 v20, 0xffff0000, v4
	v_lshlrev_b32_e32 v21, 16, v4
	v_pk_add_f32 v[80:81], v[82:83], v[80:81]
	v_pk_mul_f32 v[82:83], v[52:53], v[52:53]
	v_and_b32_e32 v72, 0xffff0000, v24
	v_lshlrev_b32_e32 v73, 16, v24
	v_and_b32_e32 v74, 0xffff0000, v26
	v_lshlrev_b32_e32 v75, 16, v26
	v_and_b32_e32 v55, 0xffff0000, v23
	v_and_b32_e32 v22, 0xffff0000, v2
	v_lshlrev_b32_e32 v23, 16, v2
	v_lshlrev_b32_e32 v24, 16, v98
	v_and_b32_e32 v26, 0xffff0000, v98
	v_lshlrev_b32_e32 v30, 16, v99
	v_and_b32_e32 v34, 0xffff0000, v99
	v_pk_mul_f32 v[98:99], v[20:21], v[20:21]
	v_pk_fma_f32 v[82:83], v[48:49], v[48:49], v[82:83]
	v_pk_fma_f32 v[118:119], v[22:23], v[22:23], v[98:99]
	v_pk_add_f32 v[98:99], v[82:83], v[80:81]
	global_load_dwordx4 v[128:131], v1, s[14:15] offset:16
	global_load_dwordx4 v[132:135], v1, s[14:15]
	global_load_dwordx4 v[136:139], v[8:9], off offset:16
	global_load_dwordx4 v[140:143], v[8:9], off
	global_load_dwordx4 v[144:147], v1, s[16:17] offset:16
	global_load_dwordx4 v[148:151], v1, s[16:17]
	global_load_dwordx4 v[152:155], v[10:11], off
	global_load_dwordx4 v[156:159], v1, s[14:15] offset:2048
	global_load_dwordx4 v[160:163], v1, s[16:17] offset:2048
	global_load_dwordx4 v[164:167], v[10:11], off offset:16
	global_load_dwordx4 v[168:171], v1, s[14:15] offset:2064
	global_load_dwordx4 v[172:175], v1, s[16:17] offset:2064
	global_load_dwordx4 v[176:179], v[12:13], off
	global_load_dwordx4 v[180:183], v19, s[14:15]
	global_load_dwordx4 v[184:187], v[12:13], off offset:16
	global_load_dwordx4 v[188:191], v19, s[14:15] offset:16
	global_load_dwordx4 v[192:195], v19, s[16:17]
	global_load_dwordx4 v[196:199], v19, s[16:17] offset:16
	global_load_dwordx4 v[200:203], v[14:15], off
	global_load_dwordx4 v[204:207], v85, s[14:15]
	global_load_dwordx4 v[208:211], v[14:15], off offset:16
	global_load_dwordx4 v[212:215], v85, s[14:15] offset:16
	global_load_dwordx4 v[216:219], v85, s[16:17]
	global_load_dwordx4 v[220:223], v85, s[16:17] offset:16
	v_and_b32_e32 v76, 0xffff0000, v25
	v_lshlrev_b32_e32 v77, 16, v25
	v_and_b32_e32 v78, 0xffff0000, v27
	v_lshlrev_b32_e32 v79, 16, v27
	v_lshlrev_b32_e32 v25, 16, v40
	v_and_b32_e32 v27, 0xffff0000, v40
	v_lshlrev_b32_e32 v37, 16, v42
	v_and_b32_e32 v39, 0xffff0000, v42
	v_lshlrev_b32_e32 v36, 16, v100
	v_and_b32_e32 v38, 0xffff0000, v100
	v_lshlrev_b32_e32 v40, 16, v101
	v_and_b32_e32 v42, 0xffff0000, v101
	v_pk_mul_f32 v[100:101], v[54:55], v[54:55]
	v_lshlrev_b32_e32 v31, 16, v41
	v_pk_fma_f32 v[100:101], v[50:51], v[50:51], v[100:101]
	v_and_b32_e32 v35, 0xffff0000, v41
	v_pk_add_f32 v[98:99], v[100:101], v[98:99]
; template <bool ZP, bool XF32, bool OUT8 = false>
; __device__ __forceinline__ void norm_phase(LAS unsigned char* lds, const void* xin, const float* gain, const float* sh, const float* sc, bf16* hout, const float* wzt, float* zout, int lane, int wave, int vcu, int G) {
;     ...
;         for (int r = 0; r < 2; ++r) { const int m = m0 + r, b = m >> 11;
;             const float rstd = rsqrtf(wave_sum(ss[r]) * (1.0f / D) + EPS);
; #pragma unroll
;             for (int j = 0; j < 4; ++j) { const int col = 512 * j + 8 * lane;
; #pragma unroll
;                 for (int q = 0; q < 2; ++q) { const f32x4 gg = *(const f32x4*)(gain + col + 4 * q), s1 = *(const f32x4*)(sc + (size_t)b * MODW + col + 4 * q), s0 = *(const f32x4*)(sh + (size_t)b * MODW + col + 4 * q);
;                     v[r][j][q] = (v[r][j][q] * rstd * gg) * (s1 + 1.0f) + s0; }
	v_pk_mul_f32 v[100:101], v[36:37], v[36:37]
	v_lshlrev_b32_e32 v41, 16, v43
	v_pk_fma_f32 v[100:101], v[24:25], v[24:25], v[100:101]
	v_and_b32_e32 v43, 0xffff0000, v43
	v_pk_add_f32 v[98:99], v[100:101], v[98:99]
	v_pk_mul_f32 v[100:101], v[38:39], v[38:39]
	v_pk_mul_f32 v[102:103], v[74:75], v[74:75]
	v_pk_fma_f32 v[100:101], v[26:27], v[26:27], v[100:101]
	v_pk_mul_f32 v[104:105], v[78:79], v[78:79]
	v_pk_add_f32 v[98:99], v[100:101], v[98:99]
	v_pk_mul_f32 v[100:101], v[40:41], v[40:41]
	v_pk_fma_f32 v[114:115], v[72:73], v[72:73], v[102:103]
	v_pk_fma_f32 v[100:101], v[30:31], v[30:31], v[100:101]
	v_pk_fma_f32 v[116:117], v[76:77], v[76:77], v[104:105]
	v_pk_add_f32 v[98:99], v[100:101], v[98:99]
	v_pk_mul_f32 v[100:101], v[42:43], v[42:43]
	v_mov_b32_e32 v122, v119
	v_pk_fma_f32 v[100:101], v[34:35], v[34:35], v[100:101]
	v_mov_b32_e32 v123, v115
	v_pk_add_f32 v[120:121], v[100:101], v[98:99]
	v_and_b32_e32 v4, 0xffff0000, v5
	v_lshlrev_b32_e32 v5, 16, v5
	v_pk_add_f32 v[120:121], v[122:123], v[120:121]
	v_and_b32_e32 v2, 0xffff0000, v3
	v_lshlrev_b32_e32 v3, 16, v3
	v_pk_mul_f32 v[122:123], v[4:5], v[4:5]
	v_mov_b32_e32 v119, v114
	v_pk_fma_f32 v[122:123], v[2:3], v[2:3], v[122:123]
	v_pk_add_f32 v[114:115], v[118:119], v[120:121]
	v_mov_b32_e32 v118, v123
	v_mov_b32_e32 v119, v117
	v_pk_add_f32 v[114:115], v[118:119], v[114:115]
	v_mov_b32_e32 v123, v116
	v_pk_add_f32 v[114:115], v[122:123], v[114:115]
	ds_bpermute_b32 v117, v84, v115
	ds_bpermute_b32 v116, v84, v114
	v_cndmask_b32_e32 v84, v86, v89, vcc
	v_lshlrev_b32_e32 v84, 2, v84
	v_cmp_lt_i32_e32 vcc, v90, v87
	v_mov_b32_e32 v124, v37
	s_waitcnt lgkmcnt(0)
	v_pk_add_f32 v[114:115], v[114:115], v[116:117]
	ds_bpermute_b32 v117, v84, v115
	ds_bpermute_b32 v116, v84, v114
	v_cndmask_b32_e32 v84, v86, v90, vcc
	v_lshlrev_b32_e32 v84, 2, v84
	v_cmp_lt_i32_e32 vcc, v91, v87
	v_mov_b32_e32 v125, v39
	s_waitcnt lgkmcnt(0)
	v_pk_add_f32 v[114:115], v[114:115], v[116:117]
	ds_bpermute_b32 v117, v84, v115
	ds_bpermute_b32 v116, v84, v114
	v_cndmask_b32_e32 v84, v86, v91, vcc
	v_lshlrev_b32_e32 v84, 2, v84
	v_cmp_lt_i32_e32 vcc, v92, v87
	v_mov_b32_e32 v122, v41
	s_waitcnt lgkmcnt(0)
	v_pk_add_f32 v[114:115], v[114:115], v[116:117]
	ds_bpermute_b32 v117, v84, v115
	ds_bpermute_b32 v116, v84, v114
	v_cndmask_b32_e32 v84, v86, v92, vcc
	v_lshlrev_b32_e32 v84, 2, v84
	v_cmp_lt_i32_e32 vcc, v93, v87
	s_waitcnt vmcnt(0)
	v_mov_b64_e32 v[94:95], v[128:129]
	v_mov_b64_e32 v[96:97], v[130:131]
	v_mov_b64_e32 v[80:81], v[132:133]
	v_mov_b64_e32 v[82:83], v[134:135]
	v_mov_b64_e32 v[98:99], v[136:137]
	v_mov_b64_e32 v[100:101], v[138:139]
	v_mov_b64_e32 v[102:103], v[140:141]
	v_mov_b64_e32 v[104:105], v[142:143]
	v_mov_b64_e32 v[106:107], v[144:145]
	v_mov_b64_e32 v[108:109], v[146:147]
	v_mov_b64_e32 v[110:111], v[148:149]
	v_mov_b64_e32 v[112:113], v[150:151]
	s_cmp_lg_u32 s3, 1
	s_cbranch_scc0 .Lnorm_nt_LBB0_937
	global_load_dwordx4 v[248:251], v[244:245], off offset:1024
	global_load_dwordx4 v[248:251], v[244:245], off offset:3072
	global_load_dwordx4 v[248:251], v[244:245], off
	global_load_dwordx4 v[248:251], v[244:245], off offset:2048
	global_load_dwordx4 v[248:251], v[246:247], off offset:1024
	global_load_dwordx4 v[248:251], v[246:247], off
	global_load_dwordx4 v[248:251], v[246:247], off offset:3072
	global_load_dwordx4 v[248:251], v[246:247], off offset:2048
.Lnorm_nt_LBB0_937:
	v_pk_add_f32 v[96:97], v[96:97], 1.0 op_sel_hi:[1,0]
	s_waitcnt lgkmcnt(0)
	v_pk_add_f32 v[114:115], v[114:115], v[116:117]
	ds_bpermute_b32 v117, v84, v115
	ds_bpermute_b32 v116, v84, v114
	v_cndmask_b32_e32 v84, v86, v93, vcc
	v_lshlrev_b32_e32 v84, 2, v84
	v_pk_add_f32 v[120:121], v[80:81], 1.0 op_sel_hi:[1,0]
	v_pk_add_f32 v[118:119], v[82:83], 1.0 op_sel_hi:[1,0]
	s_waitcnt lgkmcnt(0)
	v_pk_add_f32 v[114:115], v[114:115], v[116:117]
	ds_bpermute_b32 v117, v84, v115
	ds_bpermute_b32 v116, v84, v114
	v_pk_add_f32 v[94:95], v[94:95], 1.0 op_sel_hi:[1,0]
	v_mov_b32_e32 v123, v43
	v_pk_mov_b32 v[76:77], v[76:77], v[76:77] op_sel:[1,0]
	v_pk_mov_b32 v[78:79], v[78:79], v[78:79] op_sel:[1,0]
	s_waitcnt lgkmcnt(0)
	v_pk_add_f32 v[80:81], v[114:115], v[116:117]
	v_mov_b32_e32 v116, v57
	v_pk_fma_f32 v[80:81], v[80:81], s[6:7], v[18:19] op_sel_hi:[1,0,0]
	v_mov_b32_e32 v117, v61
	v_mul_f32_e32 v82, 0x4b800000, v81
	v_cmp_gt_f32_e32 vcc, s26, v81
	v_mov_b32_e32 v114, v67
	v_mov_b32_e32 v115, v69
	v_cndmask_b32_e32 v81, v81, v82, vcc
	v_rsq_f32_e32 v81, v81
	v_lshl_add_u64 v[82:83], v[16:17], 0, s[12:13]
	s_add_u32 s12, s7, s0
	s_addc_u32 s13, s18, s1
	v_mul_f32_e32 v84, 0x45800000, v81
	v_cndmask_b32_e32 v84, v81, v84, vcc
	v_pk_mul_f32 v[116:117], v[84:85], v[116:117] op_sel_hi:[0,1]
	v_pk_mul_f32 v[114:115], v[84:85], v[114:115] op_sel_hi:[0,1]
	v_pk_mul_f32 v[124:125], v[84:85], v[124:125] op_sel_hi:[0,1]
	v_pk_mul_f32 v[122:123], v[84:85], v[122:123] op_sel_hi:[0,1]
	v_pk_mul_f32 v[78:79], v[84:85], v[78:79] op_sel_hi:[0,1]
	v_cmp_gt_f32_e32 vcc, s26, v80
	v_mov_b32_e32 v67, v68
	v_pk_mul_f32 v[102:103], v[102:103], v[116:117]
	v_pk_mul_f32 v[104:105], v[104:105], v[114:115]
	v_pk_fma_f32 v[102:103], v[120:121], v[102:103], v[110:111]
	v_pk_fma_f32 v[104:105], v[118:119], v[104:105], v[112:113]
	v_mov_b32_e32 v110, v65
	v_mov_b32_e32 v111, v71
	v_mov_b32_e32 v112, v59
	v_mov_b32_e32 v113, v63
	v_bfe_u32 v57, v102, 16, 1
	v_pk_mul_f32 v[110:111], v[84:85], v[110:111] op_sel_hi:[0,1]
	v_pk_mul_f32 v[112:113], v[84:85], v[112:113] op_sel_hi:[0,1]
	v_add3_u32 v57, v102, v57, s27
	v_bfe_u32 v59, v103, 16, 1
	v_pk_mul_f32 v[98:99], v[98:99], v[112:113]
	v_pk_mul_f32 v[100:101], v[100:101], v[110:111]
; __device__ __forceinline__ unsigned pk2(float lo, float hi) { return f2bf(lo) | (f2bf(hi) << 16); }
; template <bool ZP, bool XF32, bool OUT8 = false>
; __device__ __forceinline__ void norm_phase(LAS unsigned char* lds, const void* xin, const float* gain, const float* sh, const float* sc, bf16* hout, const float* wzt, float* zout, int lane, int wave, int vcu, int G) {
;     ...
;             for (int j = 0; j < 4; ++j) { const int col = 512 * j + 8 * lane;
; #pragma unroll
;                 for (int q = 0; q < 2; ++q) { const f32x4 gg = *(const f32x4*)(gain + col + 4 * q), s1 = *(const f32x4*)(sc + (size_t)b * MODW + col + 4 * q), s0 = *(const f32x4*)(sh + (size_t)b * MODW + col + 4 * q);
;                     v[r][j][q] = (v[r][j][q] * rstd * gg) * (s1 + 1.0f) + s0; }
;                 if constexpr (OUT8) { *(v2u*)((unsigned char*)hout + (size_t)m * D + col) = pack8_fp8(v[r][j][0][0], v[r][j][0][1], v[r][j][0][2], v[r][j][0][3], v[r][j][1][0], v[r][j][1][1], v[r][j][1][2], v[r][j][1][3], FP8_ASCALE); }
;                 else { v4u o; o.x = pk2(v[r][j][0][0], v[r][j][0][1]); o.y = pk2(v[r][j][0][2], v[r][j][0][3]); o.z = pk2(v[r][j][1][0], v[r][j][1][1]); o.w = pk2(v[r][j][1][2], v[r][j][1][3]);
;                     *(v4u*)(hout + (size_t)m * D + col) = o; } }
	v_lshrrev_b32_e32 v57, 16, v57
	v_add3_u32 v59, v103, v59, s27
	v_pk_fma_f32 v[100:101], v[96:97], v[100:101], v[108:109]
	v_pk_fma_f32 v[96:97], v[94:95], v[98:99], v[106:107]
	v_and_or_b32 v94, v59, s25, v57
	v_bfe_u32 v57, v104, 16, 1
	v_add3_u32 v57, v104, v57, s27
	v_bfe_u32 v59, v105, 16, 1
	v_lshrrev_b32_e32 v57, 16, v57
	v_add3_u32 v59, v105, v59, s27
	v_and_or_b32 v95, v59, s25, v57
	v_bfe_u32 v57, v96, 16, 1
	v_add3_u32 v57, v96, v57, s27
	v_bfe_u32 v59, v97, 16, 1
	v_lshrrev_b32_e32 v57, 16, v57
	v_add3_u32 v59, v97, v59, s27
	v_and_or_b32 v96, v59, s25, v57
	v_bfe_u32 v57, v100, 16, 1
	v_add3_u32 v57, v100, v57, s27
	v_bfe_u32 v59, v101, 16, 1
	v_lshrrev_b32_e32 v57, 16, v57
	v_add3_u32 v59, v101, v59, s27
	v_and_or_b32 v97, v59, s25, v57
	global_store_dwordx4 v[82:83], v[94:97], off
	s_nop 1
	v_mov_b64_e32 v[94:95], v[152:153]
	v_mov_b64_e32 v[96:97], v[154:155]
	s_nop 0
	s_nop 1
	v_mov_b64_e32 v[98:99], v[156:157]
	v_mov_b64_e32 v[100:101], v[158:159]
	v_mov_b64_e32 v[102:103], v[160:161]
	v_mov_b64_e32 v[104:105], v[162:163]
	v_mov_b64_e32 v[106:107], v[164:165]
	v_mov_b64_e32 v[108:109], v[166:167]
	v_mov_b64_e32 v[110:111], v[168:169]
	v_mov_b64_e32 v[112:113], v[170:171]
	v_mov_b64_e32 v[114:115], v[172:173]
	v_mov_b64_e32 v[116:117], v[174:175]
	v_mov_b32_e32 v120, v45
	v_mov_b32_e32 v121, v29
	v_pk_mul_f32 v[120:121], v[84:85], v[120:121] op_sel_hi:[0,1]
	v_mov_b32_e32 v118, v49
	v_mov_b32_e32 v119, v51
	v_pk_mul_f32 v[118:119], v[84:85], v[118:119] op_sel_hi:[0,1]
	v_mov_b32_e32 v65, v70
	v_mov_b32_e32 v59, v62
	v_mov_b32_e32 v57, v60
	v_mov_b32_e32 v49, v50
	v_mov_b32_e32 v45, v28
	v_pk_mov_b32 v[2:3], v[2:3], v[2:3] op_sel:[1,0]
	v_pk_mov_b32 v[4:5], v[4:5], v[4:5] op_sel:[1,0]
	s_add_i32 s24, s24, 1
	s_addk_i32 s23, 0x200
	s_add_i32 s3, s3, -1
	s_cmp_eq_u32 s3, 0
	v_pk_mul_f32 v[94:95], v[94:95], v[120:121]
	v_pk_add_f32 v[98:99], v[98:99], 1.0 op_sel_hi:[1,0]
	v_pk_mul_f32 v[96:97], v[96:97], v[118:119]
	v_pk_fma_f32 v[94:95], v[98:99], v[94:95], v[102:103]
	v_pk_add_f32 v[100:101], v[100:101], 1.0 op_sel_hi:[1,0]
	v_bfe_u32 v29, v94, 16, 1
	v_pk_fma_f32 v[96:97], v[100:101], v[96:97], v[104:105]
	v_mov_b32_e32 v101, v33
	v_add3_u32 v29, v94, v29, s27
	v_bfe_u32 v33, v95, 16, 1
	v_mov_b32_e32 v100, v47
	v_lshrrev_b32_e32 v29, 16, v29
	v_add3_u32 v33, v95, v33, s27
	v_pk_mul_f32 v[100:101], v[84:85], v[100:101] op_sel_hi:[0,1]
	v_and_or_b32 v94, v33, s25, v29
	v_bfe_u32 v29, v96, 16, 1
	v_pk_mul_f32 v[100:101], v[106:107], v[100:101]
	v_pk_add_f32 v[104:105], v[110:111], 1.0 op_sel_hi:[1,0]
	v_add3_u32 v29, v96, v29, s27
	v_bfe_u32 v33, v97, 16, 1
	v_mov_b32_e32 v98, v53
	v_mov_b32_e32 v99, v55
	v_pk_fma_f32 v[100:101], v[104:105], v[100:101], v[114:115]
	v_lshrrev_b32_e32 v29, 16, v29
	v_add3_u32 v33, v97, v33, s27
	v_pk_mul_f32 v[98:99], v[84:85], v[98:99] op_sel_hi:[0,1]
	v_and_or_b32 v95, v33, s25, v29
	v_bfe_u32 v29, v100, 16, 1
	v_pk_mul_f32 v[98:99], v[108:109], v[98:99]
	v_pk_add_f32 v[102:103], v[112:113], 1.0 op_sel_hi:[1,0]
	v_add3_u32 v29, v100, v29, s27
	v_bfe_u32 v33, v101, 16, 1
	v_pk_fma_f32 v[98:99], v[102:103], v[98:99], v[116:117]
	v_lshrrev_b32_e32 v29, 16, v29
	v_add3_u32 v33, v101, v33, s27
	v_and_or_b32 v96, v33, s25, v29
	v_bfe_u32 v29, v98, 16, 1
	v_add3_u32 v29, v98, v29, s27
	v_bfe_u32 v33, v99, 16, 1
	v_lshrrev_b32_e32 v29, 16, v29
	v_add3_u32 v33, v99, v33, s27
	v_and_or_b32 v97, v33, s25, v29
	global_store_dwordx4 v[82:83], v[94:97], off offset:1024
	s_nop 1
	v_mov_b64_e32 v[94:95], v[176:177]
	v_mov_b64_e32 v[96:97], v[178:179]
	s_nop 0
	s_nop 1
	v_mov_b64_e32 v[98:99], v[180:181]
	v_mov_b64_e32 v[100:101], v[182:183]
	v_mov_b64_e32 v[102:103], v[184:185]
	v_mov_b64_e32 v[104:105], v[186:187]
	v_mov_b64_e32 v[106:107], v[188:189]
	v_mov_b64_e32 v[108:109], v[190:191]
	v_mov_b64_e32 v[110:111], v[192:193]
	v_mov_b64_e32 v[112:113], v[194:195]
	v_mov_b64_e32 v[114:115], v[196:197]
	v_mov_b64_e32 v[116:117], v[198:199]
	v_mov_b32_e32 v120, v25
	v_mov_b32_e32 v121, v27
	v_pk_mul_f32 v[120:121], v[84:85], v[120:121] op_sel_hi:[0,1]
	v_mov_b32_e32 v118, v31
	v_mov_b32_e32 v119, v35
	v_pk_mul_f32 v[118:119], v[84:85], v[118:119] op_sel_hi:[0,1]
	v_mov_b32_e32 v53, v54
	v_mov_b32_e32 v47, v32
	v_pk_mul_f32 v[94:95], v[94:95], v[120:121]
	v_pk_add_f32 v[98:99], v[98:99], 1.0 op_sel_hi:[1,0]
	v_pk_mul_f32 v[96:97], v[96:97], v[118:119]
	v_pk_add_f32 v[100:101], v[100:101], 1.0 op_sel_hi:[1,0]
	v_pk_fma_f32 v[94:95], v[98:99], v[94:95], v[110:111]
	v_pk_fma_f32 v[96:97], v[100:101], v[96:97], v[112:113]
	v_bfe_u32 v25, v94, 16, 1
	v_bfe_u32 v27, v95, 16, 1
	v_add3_u32 v25, v94, v25, s27
	v_lshrrev_b32_e32 v25, 16, v25
	v_add3_u32 v27, v95, v27, s27
	v_and_or_b32 v94, v27, s25, v25
	v_bfe_u32 v25, v96, 16, 1
	v_pk_mul_f32 v[102:103], v[102:103], v[124:125]
	v_pk_add_f32 v[106:107], v[106:107], 1.0 op_sel_hi:[1,0]
	v_add3_u32 v25, v96, v25, s27
	v_bfe_u32 v27, v97, 16, 1
	v_pk_fma_f32 v[100:101], v[106:107], v[102:103], v[114:115]
	v_lshrrev_b32_e32 v25, 16, v25
	v_add3_u32 v27, v97, v27, s27
	v_and_or_b32 v95, v27, s25, v25
	v_bfe_u32 v25, v100, 16, 1
	v_pk_mul_f32 v[104:105], v[104:105], v[122:123]
	v_pk_add_f32 v[108:109], v[108:109], 1.0 op_sel_hi:[1,0]
	v_add3_u32 v25, v100, v25, s27
	v_bfe_u32 v27, v101, 16, 1
	v_pk_fma_f32 v[98:99], v[108:109], v[104:105], v[116:117]
	v_lshrrev_b32_e32 v25, 16, v25
	v_add3_u32 v27, v101, v27, s27
	v_and_or_b32 v96, v27, s25, v25
	v_bfe_u32 v25, v98, 16, 1
	v_add3_u32 v25, v98, v25, s27
	v_bfe_u32 v27, v99, 16, 1
	v_lshrrev_b32_e32 v25, 16, v25
	v_add3_u32 v27, v99, v27, s27
	v_and_or_b32 v97, v27, s25, v25
	global_store_dwordx4 v[82:83], v[94:97], off offset:2048
; __device__ __forceinline__ unsigned pk2(float lo, float hi) { return f2bf(lo) | (f2bf(hi) << 16); }
; template <bool ZP, bool XF32, bool OUT8 = false>
; __device__ __forceinline__ void norm_phase(LAS unsigned char* lds, const void* xin, const float* gain, const float* sh, const float* sc, bf16* hout, const float* wzt, float* zout, int lane, int wave, int vcu, int G) {
;     ...
;         for (int r = 0; r < 2; ++r) { const int m = m0 + r, b = m >> 11;
;             const float rstd = rsqrtf(wave_sum(ss[r]) * (1.0f / D) + EPS);
; #pragma unroll
;             for (int j = 0; j < 4; ++j) { const int col = 512 * j + 8 * lane;
; #pragma unroll
;                 for (int q = 0; q < 2; ++q) { const f32x4 gg = *(const f32x4*)(gain + col + 4 * q), s1 = *(const f32x4*)(sc + (size_t)b * MODW + col + 4 * q), s0 = *(const f32x4*)(sh + (size_t)b * MODW + col + 4 * q);
;                     v[r][j][q] = (v[r][j][q] * rstd * gg) * (s1 + 1.0f) + s0; }
;                 if constexpr (OUT8) { *(v2u*)((unsigned char*)hout + (size_t)m * D + col) = pack8_fp8(v[r][j][0][0], v[r][j][0][1], v[r][j][0][2], v[r][j][0][3], v[r][j][1][0], v[r][j][1][1], v[r][j][1][2], v[r][j][1][3], FP8_ASCALE); }
;                 else { v4u o; o.x = pk2(v[r][j][0][0], v[r][j][0][1]); o.y = pk2(v[r][j][0][2], v[r][j][0][3]); o.z = pk2(v[r][j][1][0], v[r][j][1][1]); o.w = pk2(v[r][j][1][2], v[r][j][1][3]);
;                     *(v4u*)(hout + (size_t)m * D + col) = o; } }
	s_nop 1
	v_mov_b64_e32 v[94:95], v[200:201]
	v_mov_b64_e32 v[96:97], v[202:203]
	s_nop 0
	s_nop 1
	v_mov_b64_e32 v[98:99], v[204:205]
	v_mov_b64_e32 v[100:101], v[206:207]
	v_mov_b64_e32 v[102:103], v[208:209]
	v_mov_b64_e32 v[104:105], v[210:211]
	v_mov_b64_e32 v[106:107], v[212:213]
	v_mov_b64_e32 v[108:109], v[214:215]
	v_mov_b64_e32 v[110:111], v[216:217]
	v_mov_b64_e32 v[112:113], v[218:219]
	v_mov_b64_e32 v[114:115], v[220:221]
	v_mov_b64_e32 v[116:117], v[222:223]
	v_mov_b32_e32 v118, v73
	v_mov_b32_e32 v119, v72
	v_mov_b32_e32 v72, v75
	v_mov_b32_e32 v73, v74
	v_pk_mul_f32 v[74:75], v[84:85], v[76:77] op_sel_hi:[0,1]
	v_pk_mul_f32 v[76:77], v[84:85], v[118:119] op_sel_hi:[0,1]
	v_pk_mul_f32 v[72:73], v[84:85], v[72:73] op_sel_hi:[0,1]
	v_pk_mul_f32 v[76:77], v[76:77], v[94:95]
	v_pk_mul_f32 v[74:75], v[74:75], v[96:97]
	v_pk_add_f32 v[94:95], v[100:101], 1.0 op_sel_hi:[1,0]
	v_pk_add_f32 v[96:97], v[98:99], 1.0 op_sel_hi:[1,0]
	v_pk_mul_f32 v[72:73], v[72:73], v[102:103]
	v_pk_mul_f32 v[78:79], v[78:79], v[104:105]
	v_pk_add_f32 v[98:99], v[108:109], 1.0 op_sel_hi:[1,0]
	v_pk_add_f32 v[100:101], v[106:107], 1.0 op_sel_hi:[1,0]
	v_pk_fma_f32 v[74:75], v[74:75], v[94:95], v[112:113]
	v_pk_fma_f32 v[76:77], v[76:77], v[96:97], v[110:111]
	v_pk_fma_f32 v[78:79], v[78:79], v[98:99], v[116:117]
	v_pk_fma_f32 v[72:73], v[72:73], v[100:101], v[114:115]
	v_bfe_u32 v25, v76, 16, 1
	v_bfe_u32 v29, v74, 16, 1
	v_bfe_u32 v33, v72, 16, 1
	v_bfe_u32 v37, v78, 16, 1
	v_bfe_u32 v27, v77, 16, 1
	v_bfe_u32 v31, v75, 16, 1
	v_bfe_u32 v35, v73, 16, 1
	v_bfe_u32 v39, v79, 16, 1
	v_add3_u32 v25, v76, v25, s27
	v_add3_u32 v29, v74, v29, s27
	v_add3_u32 v33, v72, v33, s27
	v_add3_u32 v37, v78, v37, s27
	v_add3_u32 v27, v77, v27, s27
	v_add3_u32 v31, v75, v31, s27
	v_add3_u32 v35, v73, v35, s27
	v_add3_u32 v39, v79, v39, s27
	v_lshrrev_b32_e32 v25, 16, v25
	v_lshrrev_b32_e32 v29, 16, v29
	v_lshrrev_b32_e32 v33, 16, v33
	v_lshrrev_b32_e32 v37, 16, v37
	v_and_or_b32 v72, v27, s25, v25
	v_and_or_b32 v73, v31, s25, v29
	v_and_or_b32 v74, v35, s25, v33
	v_and_or_b32 v75, v39, s25, v37
	global_store_dwordx4 v[82:83], v[72:75], off offset:3072
	s_nop 1
	v_mov_b64_e32 v[74:75], v[140:141]
	v_mov_b64_e32 v[76:77], v[142:143]
	s_nop 0
	s_nop 1
	v_mov_b64_e32 v[94:95], v[132:133]
	v_mov_b64_e32 v[96:97], v[134:135]
	v_mov_b64_e32 v[98:99], v[136:137]
	v_mov_b64_e32 v[100:101], v[138:139]
	v_mov_b64_e32 v[102:103], v[128:129]
	v_mov_b64_e32 v[104:105], v[130:131]
	v_mov_b64_e32 v[106:107], v[148:149]
	v_mov_b64_e32 v[108:109], v[150:151]
	v_mov_b64_e32 v[110:111], v[144:145]
	v_mov_b64_e32 v[112:113], v[146:147]
	v_mul_f32_e32 v25, 0x4b800000, v80
	v_cndmask_b32_e32 v25, v80, v25, vcc
	v_rsq_f32_e32 v25, v25
	v_lshl_add_u64 v[72:73], v[16:17], 0, s[8:9]
	s_cselect_b64 s[8:9], -1, 0
	v_mul_f32_e32 v27, 0x45800000, v25
	v_cndmask_b32_e32 v60, v25, v27, vcc
	v_pk_mul_f32 v[62:63], v[60:61], v[66:67] op_sel_hi:[0,1]
	v_pk_mul_f32 v[56:57], v[60:61], v[56:57] op_sel_hi:[0,1]
	v_pk_mul_f32 v[64:65], v[60:61], v[64:65] op_sel_hi:[0,1]
	v_pk_mul_f32 v[58:59], v[60:61], v[58:59] op_sel_hi:[0,1]
	v_pk_mul_f32 v[46:47], v[60:61], v[46:47] op_sel_hi:[0,1]
	v_pk_mul_f32 v[2:3], v[60:61], v[2:3] op_sel_hi:[0,1]
	v_pk_mul_f32 v[4:5], v[60:61], v[4:5] op_sel_hi:[0,1]
	v_pk_add_f32 v[66:67], v[96:97], 1.0 op_sel_hi:[1,0]
	v_pk_mul_f32 v[56:57], v[74:75], v[56:57]
	v_pk_mul_f32 v[62:63], v[76:77], v[62:63]
	v_pk_add_f32 v[68:69], v[94:95], 1.0 op_sel_hi:[1,0]
	v_pk_mul_f32 v[58:59], v[98:99], v[58:59]
	v_pk_mul_f32 v[64:65], v[100:101], v[64:65]
	v_pk_add_f32 v[70:71], v[104:105], 1.0 op_sel_hi:[1,0]
	v_pk_add_f32 v[74:75], v[102:103], 1.0 op_sel_hi:[1,0]
	v_pk_fma_f32 v[62:63], v[66:67], v[62:63], v[108:109]
	v_pk_fma_f32 v[56:57], v[68:69], v[56:57], v[106:107]
	v_pk_fma_f32 v[64:65], v[70:71], v[64:65], v[112:113]
	v_pk_fma_f32 v[58:59], v[74:75], v[58:59], v[110:111]
	v_bfe_u32 v25, v56, 16, 1
	v_bfe_u32 v29, v62, 16, 1
	v_bfe_u32 v33, v58, 16, 1
	v_bfe_u32 v37, v64, 16, 1
	v_bfe_u32 v27, v57, 16, 1
	v_bfe_u32 v31, v63, 16, 1
	v_bfe_u32 v35, v59, 16, 1
	v_bfe_u32 v39, v65, 16, 1
	v_add3_u32 v25, v56, v25, s27
	v_add3_u32 v29, v62, v29, s27
	v_add3_u32 v33, v58, v33, s27
	v_add3_u32 v37, v64, v37, s27
	v_add3_u32 v27, v57, v27, s27
	v_add3_u32 v31, v63, v31, s27
	v_add3_u32 v35, v59, v35, s27
	v_add3_u32 v39, v65, v39, s27
	v_lshrrev_b32_e32 v25, 16, v25
	v_lshrrev_b32_e32 v29, 16, v29
	v_lshrrev_b32_e32 v33, 16, v33
	v_lshrrev_b32_e32 v37, 16, v37
	v_and_or_b32 v56, v27, s25, v25
	v_and_or_b32 v57, v31, s25, v29
	v_and_or_b32 v58, v35, s25, v33
	v_and_or_b32 v59, v39, s25, v37
	global_store_dwordx4 v[72:73], v[56:59], off
	s_nop 1
	v_mov_b64_e32 v[56:57], v[152:153]
	v_mov_b64_e32 v[58:59], v[154:155]
	s_nop 0
	s_nop 1
	v_mov_b64_e32 v[62:63], v[156:157]
	v_mov_b64_e32 v[64:65], v[158:159]
	v_mov_b64_e32 v[66:67], v[164:165]
	v_mov_b64_e32 v[68:69], v[166:167]
	v_mov_b64_e32 v[74:75], v[168:169]
	v_mov_b64_e32 v[76:77], v[170:171]
	v_mov_b64_e32 v[78:79], v[160:161]
	v_mov_b64_e32 v[80:81], v[162:163]
	v_mov_b64_e32 v[94:95], v[172:173]
	v_mov_b64_e32 v[96:97], v[174:175]
	v_pk_mul_f32 v[28:29], v[60:61], v[48:49] op_sel_hi:[0,1]
	v_pk_mul_f32 v[32:33], v[60:61], v[44:45] op_sel_hi:[0,1]
	v_pk_mul_f32 v[44:45], v[60:61], v[52:53] op_sel_hi:[0,1]
	v_pk_mul_f32 v[32:33], v[56:57], v[32:33]
	v_pk_mul_f32 v[28:29], v[58:59], v[28:29]
	v_pk_add_f32 v[48:49], v[64:65], 1.0 op_sel_hi:[1,0]
; __device__ __forceinline__ unsigned pk2(float lo, float hi) { return f2bf(lo) | (f2bf(hi) << 16); }
; template <bool ZP, bool XF32, bool OUT8 = false>
; __device__ __forceinline__ void norm_phase(LAS unsigned char* lds, const void* xin, const float* gain, const float* sh, const float* sc, bf16* hout, const float* wzt, float* zout, int lane, int wave, int vcu, int G) {
;     ...
;             for (int j = 0; j < 4; ++j) { const int col = 512 * j + 8 * lane;
; #pragma unroll
;                 for (int q = 0; q < 2; ++q) { const f32x4 gg = *(const f32x4*)(gain + col + 4 * q), s1 = *(const f32x4*)(sc + (size_t)b * MODW + col + 4 * q), s0 = *(const f32x4*)(sh + (size_t)b * MODW + col + 4 * q);
;                     v[r][j][q] = (v[r][j][q] * rstd * gg) * (s1 + 1.0f) + s0; }
;                 if constexpr (OUT8) { *(v2u*)((unsigned char*)hout + (size_t)m * D + col) = pack8_fp8(v[r][j][0][0], v[r][j][0][1], v[r][j][0][2], v[r][j][0][3], v[r][j][1][0], v[r][j][1][1], v[r][j][1][2], v[r][j][1][3], FP8_ASCALE); }
;                 else { v4u o; o.x = pk2(v[r][j][0][0], v[r][j][0][1]); o.y = pk2(v[r][j][0][2], v[r][j][0][3]); o.z = pk2(v[r][j][1][0], v[r][j][1][1]); o.w = pk2(v[r][j][1][2], v[r][j][1][3]);
;                     *(v4u*)(hout + (size_t)m * D + col) = o; } }
	v_pk_add_f32 v[50:51], v[62:63], 1.0 op_sel_hi:[1,0]
	v_pk_mul_f32 v[46:47], v[66:67], v[46:47]
	v_pk_mul_f32 v[44:45], v[68:69], v[44:45]
	v_pk_add_f32 v[52:53], v[76:77], 1.0 op_sel_hi:[1,0]
	v_pk_add_f32 v[54:55], v[74:75], 1.0 op_sel_hi:[1,0]
	v_pk_fma_f32 v[28:29], v[48:49], v[28:29], v[80:81]
	v_pk_fma_f32 v[32:33], v[50:51], v[32:33], v[78:79]
	v_pk_fma_f32 v[44:45], v[52:53], v[44:45], v[96:97]
	v_pk_fma_f32 v[46:47], v[54:55], v[46:47], v[94:95]
	v_bfe_u32 v25, v32, 16, 1
	v_bfe_u32 v27, v33, 16, 1
	v_bfe_u32 v31, v28, 16, 1
	v_bfe_u32 v37, v46, 16, 1
	v_bfe_u32 v41, v44, 16, 1
	v_bfe_u32 v35, v29, 16, 1
	v_bfe_u32 v39, v47, 16, 1
	v_bfe_u32 v43, v45, 16, 1
	v_add3_u32 v25, v32, v25, s27
	v_add3_u32 v27, v33, v27, s27
	v_add3_u32 v28, v28, v31, s27
	v_add3_u32 v31, v46, v37, s27
	v_add3_u32 v33, v44, v41, s27
	v_add3_u32 v29, v29, v35, s27
	v_add3_u32 v32, v47, v39, s27
	v_add3_u32 v35, v45, v43, s27
	v_lshrrev_b32_e32 v25, 16, v25
	v_lshrrev_b32_e32 v28, 16, v28
	v_lshrrev_b32_e32 v31, 16, v31
	v_lshrrev_b32_e32 v33, 16, v33
	v_and_or_b32 v44, v27, s25, v25
	v_and_or_b32 v45, v29, s25, v28
	v_and_or_b32 v46, v32, s25, v31
	v_and_or_b32 v47, v35, s25, v33
	global_store_dwordx4 v[72:73], v[44:47], off offset:1024
	s_nop 1
	v_mov_b64_e32 v[44:45], v[176:177]
	v_mov_b64_e32 v[46:47], v[178:179]
	s_nop 0
	s_nop 1
	v_mov_b64_e32 v[48:49], v[180:181]
	v_mov_b64_e32 v[50:51], v[182:183]
	v_mov_b64_e32 v[52:53], v[184:185]
	v_mov_b64_e32 v[54:55], v[186:187]
	v_mov_b64_e32 v[56:57], v[188:189]
	v_mov_b64_e32 v[58:59], v[190:191]
	v_mov_b64_e32 v[62:63], v[192:193]
	v_mov_b64_e32 v[64:65], v[194:195]
	v_mov_b64_e32 v[66:67], v[196:197]
	v_mov_b64_e32 v[68:69], v[198:199]
	v_mov_b32_e32 v41, v42
	v_mov_b32_e32 v37, v38
	v_mov_b32_e32 v31, v34
	v_mov_b32_e32 v25, v26
	v_pk_mul_f32 v[26:27], v[60:61], v[30:31] op_sel_hi:[0,1]
	v_pk_mul_f32 v[24:25], v[60:61], v[24:25] op_sel_hi:[0,1]
	v_pk_mul_f32 v[28:29], v[60:61], v[40:41] op_sel_hi:[0,1]
	v_pk_mul_f32 v[30:31], v[60:61], v[36:37] op_sel_hi:[0,1]
	v_pk_mul_f32 v[24:25], v[24:25], v[44:45]
	v_pk_mul_f32 v[26:27], v[26:27], v[46:47]
	v_pk_add_f32 v[32:33], v[50:51], 1.0 op_sel_hi:[1,0]
	v_pk_add_f32 v[34:35], v[48:49], 1.0 op_sel_hi:[1,0]
	v_pk_mul_f32 v[30:31], v[30:31], v[52:53]
	v_pk_mul_f32 v[28:29], v[28:29], v[54:55]
	v_pk_add_f32 v[36:37], v[58:59], 1.0 op_sel_hi:[1,0]
	v_pk_add_f32 v[38:39], v[56:57], 1.0 op_sel_hi:[1,0]
	v_pk_fma_f32 v[26:27], v[26:27], v[32:33], v[64:65]
	v_pk_fma_f32 v[24:25], v[24:25], v[34:35], v[62:63]
	v_pk_fma_f32 v[28:29], v[28:29], v[36:37], v[68:69]
	v_pk_fma_f32 v[30:31], v[30:31], v[38:39], v[66:67]
	v_bfe_u32 v32, v24, 16, 1
	v_bfe_u32 v34, v26, 16, 1
	v_bfe_u32 v36, v30, 16, 1
	v_bfe_u32 v38, v28, 16, 1
	v_bfe_u32 v33, v25, 16, 1
	v_bfe_u32 v35, v27, 16, 1
	v_bfe_u32 v37, v31, 16, 1
	v_bfe_u32 v39, v29, 16, 1
	v_add3_u32 v24, v24, v32, s27
	v_add3_u32 v26, v26, v34, s27
	v_add3_u32 v30, v30, v36, s27
	v_add3_u32 v28, v28, v38, s27
	v_add3_u32 v25, v25, v33, s27
	v_add3_u32 v27, v27, v35, s27
	v_add3_u32 v31, v31, v37, s27
	v_add3_u32 v29, v29, v39, s27
	v_lshrrev_b32_e32 v24, 16, v24
	v_lshrrev_b32_e32 v26, 16, v26
	v_lshrrev_b32_e32 v30, 16, v30
	v_lshrrev_b32_e32 v28, 16, v28
	v_and_or_b32 v24, v25, s25, v24
	v_and_or_b32 v25, v27, s25, v26
	v_and_or_b32 v26, v31, s25, v30
	v_and_or_b32 v27, v29, s25, v28
	global_store_dwordx4 v[72:73], v[24:27], off offset:2048
	s_nop 1
	v_mov_b64_e32 v[24:25], v[200:201]
	v_mov_b64_e32 v[26:27], v[202:203]
	s_nop 0
	s_nop 1
	v_mov_b64_e32 v[28:29], v[204:205]
	v_mov_b64_e32 v[30:31], v[206:207]
	v_mov_b64_e32 v[32:33], v[208:209]
	v_mov_b64_e32 v[34:35], v[210:211]
	v_mov_b64_e32 v[36:37], v[212:213]
	v_mov_b64_e32 v[38:39], v[214:215]
	v_mov_b64_e32 v[40:41], v[216:217]
	v_mov_b64_e32 v[42:43], v[218:219]
	v_mov_b64_e32 v[44:45], v[220:221]
	v_mov_b64_e32 v[46:47], v[222:223]
	v_mov_b32_e32 v48, v23
	v_mov_b32_e32 v49, v22
	v_mov_b32_e32 v22, v21
	v_mov_b32_e32 v23, v20
	v_pk_mul_f32 v[20:21], v[60:61], v[48:49] op_sel_hi:[0,1]
	v_pk_mul_f32 v[22:23], v[60:61], v[22:23] op_sel_hi:[0,1]
	v_pk_mul_f32 v[20:21], v[20:21], v[24:25]
	v_pk_mul_f32 v[2:3], v[2:3], v[26:27]
	v_pk_add_f32 v[24:25], v[30:31], 1.0 op_sel_hi:[1,0]
	v_pk_add_f32 v[26:27], v[28:29], 1.0 op_sel_hi:[1,0]
	v_pk_mul_f32 v[22:23], v[22:23], v[32:33]
	v_pk_mul_f32 v[4:5], v[4:5], v[34:35]
	v_pk_add_f32 v[28:29], v[38:39], 1.0 op_sel_hi:[1,0]
	v_pk_add_f32 v[30:31], v[36:37], 1.0 op_sel_hi:[1,0]
	v_pk_fma_f32 v[2:3], v[2:3], v[24:25], v[42:43]
	v_pk_fma_f32 v[20:21], v[20:21], v[26:27], v[40:41]
	v_pk_fma_f32 v[4:5], v[4:5], v[28:29], v[46:47]
	v_pk_fma_f32 v[22:23], v[22:23], v[30:31], v[44:45]
	v_bfe_u32 v24, v20, 16, 1
	v_bfe_u32 v26, v2, 16, 1
	v_bfe_u32 v28, v22, 16, 1
	v_bfe_u32 v30, v4, 16, 1
	v_bfe_u32 v25, v21, 16, 1
	v_bfe_u32 v27, v3, 16, 1
	v_bfe_u32 v29, v23, 16, 1
	v_bfe_u32 v31, v5, 16, 1
	v_add3_u32 v20, v20, v24, s27
	v_add3_u32 v2, v2, v26, s27
	v_add3_u32 v22, v22, v28, s27
	v_add3_u32 v4, v4, v30, s27
	v_add3_u32 v21, v21, v25, s27
	v_add3_u32 v3, v3, v27, s27
	v_add3_u32 v23, v23, v29, s27
	v_add3_u32 v5, v5, v31, s27
	v_lshrrev_b32_e32 v20, 16, v20
	v_lshrrev_b32_e32 v24, 16, v2
	v_lshrrev_b32_e32 v22, 16, v22
	v_lshrrev_b32_e32 v25, 16, v4
	v_and_or_b32 v2, v21, s25, v20
	v_and_or_b32 v3, v3, s25, v24
	v_and_or_b32 v4, v23, s25, v22
	v_and_or_b32 v5, v5, s25, v25
	global_store_dwordx4 v[72:73], v[2:5], off offset:3072
	s_branch .LBB0_936
